# FNet-sample epilogue: gate vectors prefetched in two batches + yh once; store-data hazard padding
# baseline (speedup 1.0000x reference)
.LBB0_725:
	s_lshl_b32 s38, s62, 8
	v_mov_b32_e32 v141, v151
	v_mov_b32_e32 v140, v150
	s_lshl_b32 s30, s62, 7
	s_lshl_b32 s31, s81, 8
	s_and_b32 s38, s38, 0x100
	s_and_b32 s30, s30, 0xffffff00
	s_or_b32 s38, s38, s87
	s_add_i32 s31, s31, s86
	v_lshl_add_u32 v140, v140, 3, s38
	s_add_i32 s31, s31, s30
	v_add_u32_e32 v142, s31, v141
	v_ashrrev_i32_e32 v141, 31, v140
	v_mov_b64_e32 v[144:145], s[24:25]
	v_mad_i64_i32 v[146:147], s[30:31], v142, s77, v[144:145]
	v_lshlrev_b64 v[140:141], 1, v[140:141]
	v_lshl_add_u64 v[146:147], v[146:147], 0, v[140:141]
	v_add_co_u32_e32 v146, vcc, s34, v146
	v_ashrrev_i32_e32 v143, 31, v142
	s_nop 0
	v_addc_co_u32_e32 v147, vcc, 0, v147, vcc
	global_load_dwordx4 v[164:167], v[146:147], off offset:1024
	global_load_dwordx4 v[168:171], v[146:147], off offset:1280
	v_add_co_u32_e32 v162, vcc, 0x28000, v146
	s_nop 1
	v_addc_co_u32_e32 v163, vcc, 0, v147, vcc
	global_load_dwordx4 v[172:175], v[162:163], off offset:1024
	global_load_dwordx4 v[176:179], v[162:163], off offset:1280
	v_add_co_u32_e32 v162, vcc, 0x50000, v146
	s_nop 1
	v_addc_co_u32_e32 v163, vcc, 0, v147, vcc
	global_load_dwordx4 v[180:183], v[162:163], off offset:1024
	global_load_dwordx4 v[184:187], v[162:163], off offset:1280
	v_add_co_u32_e32 v162, vcc, 0x78000, v146
	s_nop 1
	v_addc_co_u32_e32 v163, vcc, 0, v147, vcc
	global_load_dwordx4 v[188:191], v[162:163], off offset:1024
	global_load_dwordx4 v[192:195], v[162:163], off offset:1280
	v_add_co_u32_e32 v162, vcc, 0x140000, v146
	s_nop 1
	v_addc_co_u32_e32 v163, vcc, 0, v147, vcc
	global_load_dwordx4 v[196:199], v[162:163], off offset:1024
	global_load_dwordx4 v[206:209], v[162:163], off offset:1280
	v_add_co_u32_e32 v162, vcc, 0x168000, v146
	s_nop 1
	v_addc_co_u32_e32 v163, vcc, 0, v147, vcc
	global_load_dwordx4 v[210:213], v[162:163], off offset:1024
	global_load_dwordx4 v[214:217], v[162:163], off offset:1280
	v_add_co_u32_e32 v162, vcc, 0x190000, v146
	s_nop 1
	v_addc_co_u32_e32 v163, vcc, 0, v147, vcc
	global_load_dwordx4 v[218:221], v[162:163], off offset:1024
	global_load_dwordx4 v[222:225], v[162:163], off offset:1280
	v_add_co_u32_e32 v162, vcc, 0x1b8000, v146
	s_nop 1
	v_addc_co_u32_e32 v163, vcc, 0, v147, vcc
	global_load_dwordx4 v[226:229], v[162:163], off offset:1024
	global_load_dwordx4 v[230:233], v[162:163], off offset:1280
	v_lshlrev_b64 v[148:149], 12, v[142:143]
	s_waitcnt vmcnt(0)
	v_mov_b32_e32 v154, v164
	v_mov_b32_e32 v155, v165
	v_mov_b32_e32 v156, v166
	v_mov_b32_e32 v157, v167
	v_lshlrev_b32_e32 v158, 16, v154
	v_mul_f32_e32 v143, 0xbfb8aa3b, v158
	v_exp_f32_e32 v143, v143
	v_and_b32_e32 v159, 0xffff0000, v154
	v_lshlrev_b32_e32 v154, 16, v155
	v_and_b32_e32 v155, 0xffff0000, v155
	v_add_f32_e32 v143, 1.0, v143
	v_rcp_f32_e32 v160, v143
	v_mul_f32_e32 v143, 0xbfb8aa3b, v159
	v_exp_f32_e32 v143, v143
	s_nop 0
	v_add_f32_e32 v143, 1.0, v143
	v_rcp_f32_e32 v161, v143
	s_nop 0
	v_pk_mul_f32 v[158:159], v[160:161], v[158:159]
	s_nop 0
	v_pk_mul_f32 v[126:127], v[126:127], v[158:159]
	s_nop 0
	v_cvt_pk_bf16_f32 v126, v126, v127
	v_mul_f32_e32 v127, 0xbfb8aa3b, v154
	v_exp_f32_e32 v127, v127
	s_nop 0
	v_add_f32_e32 v127, 1.0, v127
	v_rcp_f32_e32 v158, v127
	v_mul_f32_e32 v127, 0xbfb8aa3b, v155
	v_exp_f32_e32 v127, v127
	s_nop 0
	v_add_f32_e32 v127, 1.0, v127
	v_rcp_f32_e32 v159, v127
	s_nop 0
	v_pk_mul_f32 v[154:155], v[158:159], v[154:155]
	s_nop 0
	v_pk_mul_f32 v[128:129], v[128:129], v[154:155]
	s_nop 0
	v_cvt_pk_bf16_f32 v127, v128, v129
	v_lshlrev_b32_e32 v128, 16, v156
	v_mul_f32_e32 v143, 0xbfb8aa3b, v128
	v_exp_f32_e32 v143, v143
	v_and_b32_e32 v129, 0xffff0000, v156
	v_add_f32_e32 v143, 1.0, v143
	v_rcp_f32_e32 v154, v143
	v_mul_f32_e32 v143, 0xbfb8aa3b, v129
	v_exp_f32_e32 v143, v143
	s_nop 0
	v_add_f32_e32 v143, 1.0, v143
	v_rcp_f32_e32 v155, v143
	s_nop 0
	v_pk_mul_f32 v[128:129], v[154:155], v[128:129]
	s_nop 0
	v_pk_mul_f32 v[122:123], v[122:123], v[128:129]
	s_nop 0
	v_cvt_pk_bf16_f32 v128, v122, v123
	v_lshlrev_b32_e32 v122, 16, v157
	v_mul_f32_e32 v129, 0xbfb8aa3b, v122
	v_exp_f32_e32 v129, v129
	v_and_b32_e32 v123, 0xffff0000, v157
	v_add_f32_e32 v129, 1.0, v129
	v_rcp_f32_e32 v154, v129
	v_mul_f32_e32 v129, 0xbfb8aa3b, v123
	v_exp_f32_e32 v129, v129
	s_nop 0
	v_add_f32_e32 v129, 1.0, v129
	v_rcp_f32_e32 v155, v129
	s_nop 0
	v_pk_mul_f32 v[122:123], v[154:155], v[122:123]
	s_nop 0
	v_pk_mul_f32 v[122:123], v[124:125], v[122:123]
	s_nop 0
	v_cvt_pk_bf16_f32 v129, v122, v123
	v_lshl_add_u64 v[122:123], s[64:65], 0, v[148:149]
	v_lshl_add_u64 v[122:123], v[122:123], 0, v[140:141]
	global_store_dwordx4 v[122:123], v[126:129], off offset:3072
	s_nop 1
	v_mov_b32_e32 v124, v168
	v_mov_b32_e32 v125, v169
	v_mov_b32_e32 v126, v170
	v_mov_b32_e32 v127, v171
	v_lshlrev_b32_e32 v128, 16, v124
	v_and_b32_e32 v129, 0xffff0000, v124
	v_mul_f32_e32 v124, 0xbfb8aa3b, v128
	v_exp_f32_e32 v124, v124
	s_nop 0
	v_add_f32_e32 v124, 1.0, v124
	v_rcp_f32_e32 v146, v124
	v_mul_f32_e32 v124, 0xbfb8aa3b, v129
	v_exp_f32_e32 v124, v124
	s_nop 0
	v_add_f32_e32 v124, 1.0, v124
	v_rcp_f32_e32 v147, v124
	v_lshlrev_b32_e32 v124, 16, v125
	v_and_b32_e32 v125, 0xffff0000, v125
	v_pk_mul_f32 v[128:129], v[146:147], v[128:129]
	s_nop 0
	v_pk_mul_f32 v[118:119], v[118:119], v[128:129]
	s_nop 0
	v_cvt_pk_bf16_f32 v118, v118, v119
	v_mul_f32_e32 v119, 0xbfb8aa3b, v124
	v_exp_f32_e32 v119, v119
	s_nop 0
	v_add_f32_e32 v119, 1.0, v119
	v_rcp_f32_e32 v128, v119
	v_mul_f32_e32 v119, 0xbfb8aa3b, v125
	v_exp_f32_e32 v119, v119
	s_nop 0
	v_add_f32_e32 v119, 1.0, v119
	v_rcp_f32_e32 v129, v119
	s_nop 0
	v_pk_mul_f32 v[124:125], v[128:129], v[124:125]
	s_nop 0
	v_pk_mul_f32 v[120:121], v[120:121], v[124:125]
	s_nop 0
	v_cvt_pk_bf16_f32 v119, v120, v121
	v_lshlrev_b32_e32 v120, 16, v126
	v_and_b32_e32 v121, 0xffff0000, v126
	v_mul_f32_e32 v124, 0xbfb8aa3b, v120
	v_mul_f32_e32 v125, 0xbfb8aa3b, v121
	v_exp_f32_e32 v124, v124
	v_exp_f32_e32 v125, v125
	v_add_f32_e32 v124, 1.0, v124
	v_add_f32_e32 v125, 1.0, v125
	v_rcp_f32_e32 v124, v124
	v_rcp_f32_e32 v125, v125
	s_nop 0
	v_pk_mul_f32 v[120:121], v[124:125], v[120:121]
	s_nop 0
	v_pk_mul_f32 v[114:115], v[114:115], v[120:121]
	s_nop 0
	v_cvt_pk_bf16_f32 v120, v114, v115
	v_lshlrev_b32_e32 v114, 16, v127
	v_mul_f32_e32 v121, 0xbfb8aa3b, v114
	v_exp_f32_e32 v121, v121
	v_and_b32_e32 v115, 0xffff0000, v127
	v_add_f32_e32 v121, 1.0, v121
	v_rcp_f32_e32 v124, v121
	v_mul_f32_e32 v121, 0xbfb8aa3b, v115
	v_exp_f32_e32 v121, v121
	s_nop 0
	v_add_f32_e32 v121, 1.0, v121
	v_rcp_f32_e32 v125, v121
	s_nop 0
	v_pk_mul_f32 v[114:115], v[124:125], v[114:115]
	s_nop 0
	v_pk_mul_f32 v[114:115], v[116:117], v[114:115]
	s_nop 0
	v_cvt_pk_bf16_f32 v121, v114, v115
	global_store_dwordx4 v[122:123], v[118:121], off offset:3328
	s_nop 1
	v_add_u32_e32 v114, 16, v142
	v_ashrrev_i32_e32 v115, 31, v114
	v_lshlrev_b64 v[116:117], 12, v[114:115]
	v_mad_i64_i32 v[114:115], s[30:31], v114, s77, v[144:145]
	v_lshl_add_u64 v[114:115], v[114:115], 0, v[140:141]
	v_add_co_u32_e32 v114, vcc, s34, v114
	s_nop 1
	v_addc_co_u32_e32 v115, vcc, 0, v115, vcc
	v_mov_b32_e32 v118, v172
	v_mov_b32_e32 v119, v173
	v_mov_b32_e32 v120, v174
	v_mov_b32_e32 v121, v175
	v_lshlrev_b32_e32 v122, 16, v118
	v_and_b32_e32 v123, 0xffff0000, v118
	v_mul_f32_e32 v118, 0xbfb8aa3b, v122
	v_exp_f32_e32 v118, v118
	s_nop 0
	v_add_f32_e32 v118, 1.0, v118
	v_rcp_f32_e32 v124, v118
	v_mul_f32_e32 v118, 0xbfb8aa3b, v123
	v_exp_f32_e32 v118, v118
	s_nop 0
	v_add_f32_e32 v118, 1.0, v118
	v_rcp_f32_e32 v125, v118
	v_lshlrev_b32_e32 v118, 16, v119
	v_and_b32_e32 v119, 0xffff0000, v119
	v_pk_mul_f32 v[122:123], v[124:125], v[122:123]
	s_nop 0
	v_pk_mul_f32 v[110:111], v[110:111], v[122:123]
	s_nop 0
	v_cvt_pk_bf16_f32 v110, v110, v111
	v_mul_f32_e32 v111, 0xbfb8aa3b, v118
	v_exp_f32_e32 v111, v111
	s_nop 0
	v_add_f32_e32 v111, 1.0, v111
	v_rcp_f32_e32 v122, v111
	v_mul_f32_e32 v111, 0xbfb8aa3b, v119
	v_exp_f32_e32 v111, v111
	s_nop 0
	v_add_f32_e32 v111, 1.0, v111
	v_rcp_f32_e32 v123, v111
	s_nop 0
	v_pk_mul_f32 v[118:119], v[122:123], v[118:119]
	s_nop 0
	v_pk_mul_f32 v[112:113], v[112:113], v[118:119]
	s_nop 0
	v_cvt_pk_bf16_f32 v111, v112, v113
	v_lshlrev_b32_e32 v112, 16, v120
	v_and_b32_e32 v113, 0xffff0000, v120
	v_mul_f32_e32 v118, 0xbfb8aa3b, v112
	v_mul_f32_e32 v119, 0xbfb8aa3b, v113
	v_exp_f32_e32 v118, v118
	v_exp_f32_e32 v119, v119
	v_add_f32_e32 v118, 1.0, v118
	v_add_f32_e32 v119, 1.0, v119
	v_rcp_f32_e32 v118, v118
	v_rcp_f32_e32 v119, v119
	s_nop 0
	v_pk_mul_f32 v[112:113], v[118:119], v[112:113]
	s_nop 0
	v_pk_mul_f32 v[106:107], v[106:107], v[112:113]
	s_nop 0
	v_cvt_pk_bf16_f32 v112, v106, v107
	v_lshlrev_b32_e32 v106, 16, v121
	v_mul_f32_e32 v113, 0xbfb8aa3b, v106
	v_exp_f32_e32 v113, v113
	v_and_b32_e32 v107, 0xffff0000, v121
	v_add_f32_e32 v113, 1.0, v113
	v_rcp_f32_e32 v118, v113
	v_mul_f32_e32 v113, 0xbfb8aa3b, v107
	v_exp_f32_e32 v113, v113
	s_nop 0
	v_add_f32_e32 v113, 1.0, v113
	v_rcp_f32_e32 v119, v113
	s_nop 0
	v_pk_mul_f32 v[106:107], v[118:119], v[106:107]
	s_nop 0
	v_pk_mul_f32 v[106:107], v[108:109], v[106:107]
	s_nop 0
	v_cvt_pk_bf16_f32 v113, v106, v107
	v_lshl_add_u64 v[106:107], s[64:65], 0, v[116:117]
	v_lshl_add_u64 v[106:107], v[106:107], 0, v[140:141]
	global_store_dwordx4 v[106:107], v[110:113], off offset:3072
	s_nop 1
	v_mov_b32_e32 v108, v176
	v_mov_b32_e32 v109, v177
	v_mov_b32_e32 v110, v178
	v_mov_b32_e32 v111, v179
	v_lshlrev_b32_e32 v112, 16, v108
	v_and_b32_e32 v113, 0xffff0000, v108
	v_mul_f32_e32 v108, 0xbfb8aa3b, v112
	v_exp_f32_e32 v108, v108
	s_nop 0
	v_add_f32_e32 v108, 1.0, v108
	v_rcp_f32_e32 v114, v108
	v_mul_f32_e32 v108, 0xbfb8aa3b, v113
	v_exp_f32_e32 v108, v108
	s_nop 0
	v_add_f32_e32 v108, 1.0, v108
	v_rcp_f32_e32 v115, v108
	v_lshlrev_b32_e32 v108, 16, v109
	v_and_b32_e32 v109, 0xffff0000, v109
	v_pk_mul_f32 v[112:113], v[114:115], v[112:113]
	s_nop 0
	v_pk_mul_f32 v[102:103], v[102:103], v[112:113]
	s_nop 0
	v_cvt_pk_bf16_f32 v102, v102, v103
	v_mul_f32_e32 v103, 0xbfb8aa3b, v108
	v_exp_f32_e32 v103, v103
	s_nop 0
	v_add_f32_e32 v103, 1.0, v103
	v_rcp_f32_e32 v112, v103
	v_mul_f32_e32 v103, 0xbfb8aa3b, v109
	v_exp_f32_e32 v103, v103
	s_nop 0
	v_add_f32_e32 v103, 1.0, v103
	v_rcp_f32_e32 v113, v103
	s_nop 0
	v_pk_mul_f32 v[108:109], v[112:113], v[108:109]
	s_nop 0
	v_pk_mul_f32 v[104:105], v[104:105], v[108:109]
	s_nop 0
	v_cvt_pk_bf16_f32 v103, v104, v105
	v_lshlrev_b32_e32 v104, 16, v110
	v_and_b32_e32 v105, 0xffff0000, v110
	v_mul_f32_e32 v108, 0xbfb8aa3b, v104
	v_mul_f32_e32 v109, 0xbfb8aa3b, v105
	v_exp_f32_e32 v108, v108
	v_exp_f32_e32 v109, v109
	v_add_f32_e32 v108, 1.0, v108
	v_add_f32_e32 v109, 1.0, v109
	v_rcp_f32_e32 v108, v108
	v_rcp_f32_e32 v109, v109
	s_nop 0
	v_pk_mul_f32 v[104:105], v[108:109], v[104:105]
	s_nop 0
	v_pk_mul_f32 v[98:99], v[98:99], v[104:105]
	s_nop 0
	v_cvt_pk_bf16_f32 v104, v98, v99
	v_lshlrev_b32_e32 v98, 16, v111
	v_mul_f32_e32 v105, 0xbfb8aa3b, v98
	v_exp_f32_e32 v105, v105
	v_and_b32_e32 v99, 0xffff0000, v111
	v_add_f32_e32 v105, 1.0, v105
	v_rcp_f32_e32 v108, v105
	v_mul_f32_e32 v105, 0xbfb8aa3b, v99
	v_exp_f32_e32 v105, v105
	s_nop 0
	v_add_f32_e32 v105, 1.0, v105
	v_rcp_f32_e32 v109, v105
	s_nop 0
	v_pk_mul_f32 v[98:99], v[108:109], v[98:99]
	s_nop 0
	v_pk_mul_f32 v[98:99], v[100:101], v[98:99]
	s_nop 0
	v_cvt_pk_bf16_f32 v105, v98, v99
	global_store_dwordx4 v[106:107], v[102:105], off offset:3328
	s_nop 1
	v_add_u32_e32 v98, 32, v142
	v_ashrrev_i32_e32 v99, 31, v98
	v_lshlrev_b64 v[100:101], 12, v[98:99]
	v_mad_i64_i32 v[98:99], s[30:31], v98, s77, v[144:145]
	v_lshl_add_u64 v[98:99], v[98:99], 0, v[140:141]
	v_add_co_u32_e32 v98, vcc, s34, v98
	s_nop 1
	v_addc_co_u32_e32 v99, vcc, 0, v99, vcc
	v_mov_b32_e32 v102, v180
	v_mov_b32_e32 v103, v181
	v_mov_b32_e32 v104, v182
	v_mov_b32_e32 v105, v183
	v_lshlrev_b32_e32 v106, 16, v102
	v_and_b32_e32 v107, 0xffff0000, v102
	v_mul_f32_e32 v102, 0xbfb8aa3b, v106
	v_exp_f32_e32 v102, v102
	s_nop 0
	v_add_f32_e32 v102, 1.0, v102
	v_rcp_f32_e32 v108, v102
	v_mul_f32_e32 v102, 0xbfb8aa3b, v107
	v_exp_f32_e32 v102, v102
	s_nop 0
	v_add_f32_e32 v102, 1.0, v102
	v_rcp_f32_e32 v109, v102
	v_lshlrev_b32_e32 v102, 16, v103
	v_and_b32_e32 v103, 0xffff0000, v103
	v_pk_mul_f32 v[106:107], v[108:109], v[106:107]
	s_nop 0
	v_pk_mul_f32 v[94:95], v[94:95], v[106:107]
	s_nop 0
	v_cvt_pk_bf16_f32 v94, v94, v95
	v_mul_f32_e32 v95, 0xbfb8aa3b, v102
	v_exp_f32_e32 v95, v95
	s_nop 0
	v_add_f32_e32 v95, 1.0, v95
	v_rcp_f32_e32 v106, v95
	v_mul_f32_e32 v95, 0xbfb8aa3b, v103
	v_exp_f32_e32 v95, v95
	s_nop 0
	v_add_f32_e32 v95, 1.0, v95
	v_rcp_f32_e32 v107, v95
	s_nop 0
	v_pk_mul_f32 v[102:103], v[106:107], v[102:103]
	s_nop 0
	v_pk_mul_f32 v[96:97], v[96:97], v[102:103]
	s_nop 0
	v_cvt_pk_bf16_f32 v95, v96, v97
	v_lshlrev_b32_e32 v96, 16, v104
	v_and_b32_e32 v97, 0xffff0000, v104
	v_mul_f32_e32 v102, 0xbfb8aa3b, v96
	v_mul_f32_e32 v103, 0xbfb8aa3b, v97
	v_exp_f32_e32 v102, v102
	v_exp_f32_e32 v103, v103
	v_add_f32_e32 v102, 1.0, v102
	v_add_f32_e32 v103, 1.0, v103
	v_rcp_f32_e32 v102, v102
	v_rcp_f32_e32 v103, v103
	s_nop 0
	v_pk_mul_f32 v[96:97], v[102:103], v[96:97]
	s_nop 0
	v_pk_mul_f32 v[90:91], v[90:91], v[96:97]
	s_nop 0
	v_cvt_pk_bf16_f32 v96, v90, v91
	v_lshlrev_b32_e32 v90, 16, v105
	v_mul_f32_e32 v97, 0xbfb8aa3b, v90
	v_exp_f32_e32 v97, v97
	v_and_b32_e32 v91, 0xffff0000, v105
	v_add_f32_e32 v97, 1.0, v97
	v_rcp_f32_e32 v102, v97
	v_mul_f32_e32 v97, 0xbfb8aa3b, v91
	v_exp_f32_e32 v97, v97
	s_nop 0
	v_add_f32_e32 v97, 1.0, v97
	v_rcp_f32_e32 v103, v97
	s_nop 0
	v_pk_mul_f32 v[90:91], v[102:103], v[90:91]
	s_nop 0
	v_pk_mul_f32 v[90:91], v[92:93], v[90:91]
	s_nop 0
	v_cvt_pk_bf16_f32 v97, v90, v91
	v_lshl_add_u64 v[90:91], s[64:65], 0, v[100:101]
	v_lshl_add_u64 v[90:91], v[90:91], 0, v[140:141]
	global_store_dwordx4 v[90:91], v[94:97], off offset:3072
	s_nop 1
	v_mov_b32_e32 v92, v184
	v_mov_b32_e32 v93, v185
	v_mov_b32_e32 v94, v186
	v_mov_b32_e32 v95, v187
	v_lshlrev_b32_e32 v96, 16, v92
	v_and_b32_e32 v97, 0xffff0000, v92
	v_mul_f32_e32 v92, 0xbfb8aa3b, v96
	v_exp_f32_e32 v92, v92
	s_nop 0
	v_add_f32_e32 v92, 1.0, v92
	v_rcp_f32_e32 v98, v92
	v_mul_f32_e32 v92, 0xbfb8aa3b, v97
	v_exp_f32_e32 v92, v92
	s_nop 0
	v_add_f32_e32 v92, 1.0, v92
	v_rcp_f32_e32 v99, v92
	v_lshlrev_b32_e32 v92, 16, v93
	v_and_b32_e32 v93, 0xffff0000, v93
	v_pk_mul_f32 v[96:97], v[98:99], v[96:97]
	s_nop 0
	v_pk_mul_f32 v[86:87], v[86:87], v[96:97]
	s_nop 0
	v_cvt_pk_bf16_f32 v86, v86, v87
	v_mul_f32_e32 v87, 0xbfb8aa3b, v92
	v_exp_f32_e32 v87, v87
	s_nop 0
	v_add_f32_e32 v87, 1.0, v87
	v_rcp_f32_e32 v96, v87
	v_mul_f32_e32 v87, 0xbfb8aa3b, v93
	v_exp_f32_e32 v87, v87
	s_nop 0
	v_add_f32_e32 v87, 1.0, v87
	v_rcp_f32_e32 v97, v87
	s_nop 0
	v_pk_mul_f32 v[92:93], v[96:97], v[92:93]
	s_nop 0
	v_pk_mul_f32 v[88:89], v[88:89], v[92:93]
	s_nop 0
	v_cvt_pk_bf16_f32 v87, v88, v89
	v_lshlrev_b32_e32 v88, 16, v94
	v_and_b32_e32 v89, 0xffff0000, v94
	v_mul_f32_e32 v92, 0xbfb8aa3b, v88
	v_mul_f32_e32 v93, 0xbfb8aa3b, v89
	v_exp_f32_e32 v92, v92
	v_exp_f32_e32 v93, v93
	v_add_f32_e32 v92, 1.0, v92
	v_add_f32_e32 v93, 1.0, v93
	v_rcp_f32_e32 v92, v92
	v_rcp_f32_e32 v93, v93
	s_nop 0
	v_pk_mul_f32 v[88:89], v[92:93], v[88:89]
	s_nop 0
	v_pk_mul_f32 v[82:83], v[82:83], v[88:89]
	s_nop 0
	v_cvt_pk_bf16_f32 v88, v82, v83
	v_lshlrev_b32_e32 v82, 16, v95
	v_mul_f32_e32 v89, 0xbfb8aa3b, v82
	v_exp_f32_e32 v89, v89
	v_and_b32_e32 v83, 0xffff0000, v95
	v_add_f32_e32 v89, 1.0, v89
	v_rcp_f32_e32 v92, v89
	v_mul_f32_e32 v89, 0xbfb8aa3b, v83
	v_exp_f32_e32 v89, v89
	s_nop 0
	v_add_f32_e32 v89, 1.0, v89
	v_rcp_f32_e32 v93, v89
	s_nop 0
	v_pk_mul_f32 v[82:83], v[92:93], v[82:83]
	s_nop 0
	v_pk_mul_f32 v[82:83], v[84:85], v[82:83]
	s_nop 0
	v_cvt_pk_bf16_f32 v89, v82, v83
	global_store_dwordx4 v[90:91], v[86:89], off offset:3328
	s_nop 1
	v_add_u32_e32 v82, 48, v142
	v_ashrrev_i32_e32 v83, 31, v82
	v_lshlrev_b64 v[84:85], 12, v[82:83]
	v_mad_i64_i32 v[82:83], s[30:31], v82, s77, v[144:145]
	v_lshl_add_u64 v[82:83], v[82:83], 0, v[140:141]
	v_add_co_u32_e32 v82, vcc, s34, v82
	s_nop 1
	v_addc_co_u32_e32 v83, vcc, 0, v83, vcc
	v_mov_b32_e32 v86, v188
	v_mov_b32_e32 v87, v189
	v_mov_b32_e32 v88, v190
	v_mov_b32_e32 v89, v191
	v_lshlrev_b32_e32 v90, 16, v86
	v_and_b32_e32 v91, 0xffff0000, v86
	v_mul_f32_e32 v86, 0xbfb8aa3b, v90
	v_exp_f32_e32 v86, v86
	s_nop 0
	v_add_f32_e32 v86, 1.0, v86
	v_rcp_f32_e32 v92, v86
	v_mul_f32_e32 v86, 0xbfb8aa3b, v91
	v_exp_f32_e32 v86, v86
	s_nop 0
	v_add_f32_e32 v86, 1.0, v86
	v_rcp_f32_e32 v93, v86
	v_lshlrev_b32_e32 v86, 16, v87
	v_and_b32_e32 v87, 0xffff0000, v87
	v_pk_mul_f32 v[90:91], v[92:93], v[90:91]
	s_nop 0
	v_pk_mul_f32 v[78:79], v[78:79], v[90:91]
	s_nop 0
	v_cvt_pk_bf16_f32 v78, v78, v79
	v_mul_f32_e32 v79, 0xbfb8aa3b, v86
	v_exp_f32_e32 v79, v79
	s_nop 0
	v_add_f32_e32 v79, 1.0, v79
	v_rcp_f32_e32 v90, v79
	v_mul_f32_e32 v79, 0xbfb8aa3b, v87
	v_exp_f32_e32 v79, v79
	s_nop 0
	v_add_f32_e32 v79, 1.0, v79
	v_rcp_f32_e32 v91, v79
	s_nop 0
	v_pk_mul_f32 v[86:87], v[90:91], v[86:87]
	s_nop 0
	v_pk_mul_f32 v[80:81], v[80:81], v[86:87]
	s_nop 0
	v_cvt_pk_bf16_f32 v79, v80, v81
	v_lshlrev_b32_e32 v80, 16, v88
	v_and_b32_e32 v81, 0xffff0000, v88
	v_mul_f32_e32 v86, 0xbfb8aa3b, v80
	v_mul_f32_e32 v87, 0xbfb8aa3b, v81
	v_exp_f32_e32 v86, v86
	v_exp_f32_e32 v87, v87
	v_add_f32_e32 v86, 1.0, v86
	v_add_f32_e32 v87, 1.0, v87
	v_rcp_f32_e32 v86, v86
	v_rcp_f32_e32 v87, v87
	s_nop 0
	v_pk_mul_f32 v[80:81], v[86:87], v[80:81]
	s_nop 0
	v_pk_mul_f32 v[74:75], v[74:75], v[80:81]
	s_nop 0
	v_cvt_pk_bf16_f32 v80, v74, v75
	v_lshlrev_b32_e32 v74, 16, v89
	v_mul_f32_e32 v81, 0xbfb8aa3b, v74
	v_exp_f32_e32 v81, v81
	v_and_b32_e32 v75, 0xffff0000, v89
	v_add_f32_e32 v81, 1.0, v81
	v_rcp_f32_e32 v86, v81
	v_mul_f32_e32 v81, 0xbfb8aa3b, v75
	v_exp_f32_e32 v81, v81
	s_nop 0
	v_add_f32_e32 v81, 1.0, v81
	v_rcp_f32_e32 v87, v81
	s_nop 0
	v_pk_mul_f32 v[74:75], v[86:87], v[74:75]
	s_nop 0
	v_pk_mul_f32 v[74:75], v[76:77], v[74:75]
	s_nop 0
	v_cvt_pk_bf16_f32 v81, v74, v75
	v_lshl_add_u64 v[74:75], s[64:65], 0, v[84:85]
	v_lshl_add_u64 v[74:75], v[74:75], 0, v[140:141]
	global_store_dwordx4 v[74:75], v[78:81], off offset:3072
	s_nop 1
	v_mov_b32_e32 v76, v192
	v_mov_b32_e32 v77, v193
	v_mov_b32_e32 v78, v194
	v_mov_b32_e32 v79, v195
	v_lshlrev_b32_e32 v80, 16, v76
	v_and_b32_e32 v81, 0xffff0000, v76
	v_mul_f32_e32 v76, 0xbfb8aa3b, v80
	v_exp_f32_e32 v76, v76
	s_nop 0
	v_add_f32_e32 v76, 1.0, v76
	v_rcp_f32_e32 v82, v76
	v_mul_f32_e32 v76, 0xbfb8aa3b, v81
	v_exp_f32_e32 v76, v76
	s_nop 0
	v_add_f32_e32 v76, 1.0, v76
	v_rcp_f32_e32 v83, v76
	v_lshlrev_b32_e32 v76, 16, v77
	v_and_b32_e32 v77, 0xffff0000, v77
	v_pk_mul_f32 v[80:81], v[82:83], v[80:81]
	s_nop 0
	v_pk_mul_f32 v[70:71], v[70:71], v[80:81]
	s_nop 0
	v_cvt_pk_bf16_f32 v70, v70, v71
	v_mul_f32_e32 v71, 0xbfb8aa3b, v76
	v_exp_f32_e32 v71, v71
	s_nop 0
	v_add_f32_e32 v71, 1.0, v71
	v_rcp_f32_e32 v80, v71
	v_mul_f32_e32 v71, 0xbfb8aa3b, v77
	v_exp_f32_e32 v71, v71
	s_nop 0
	v_add_f32_e32 v71, 1.0, v71
	v_rcp_f32_e32 v81, v71
	s_nop 0
	v_pk_mul_f32 v[76:77], v[80:81], v[76:77]
	s_nop 0
	v_pk_mul_f32 v[72:73], v[72:73], v[76:77]
	s_nop 0
	v_cvt_pk_bf16_f32 v71, v72, v73
	v_lshlrev_b32_e32 v72, 16, v78
	v_and_b32_e32 v73, 0xffff0000, v78
	v_mul_f32_e32 v76, 0xbfb8aa3b, v72
	v_mul_f32_e32 v77, 0xbfb8aa3b, v73
	v_exp_f32_e32 v76, v76
	v_exp_f32_e32 v77, v77
	v_add_f32_e32 v76, 1.0, v76
	v_add_f32_e32 v77, 1.0, v77
	v_rcp_f32_e32 v76, v76
	v_rcp_f32_e32 v77, v77
	s_nop 0
	v_pk_mul_f32 v[72:73], v[76:77], v[72:73]
	s_nop 0
	v_pk_mul_f32 v[66:67], v[66:67], v[72:73]
	s_nop 0
	v_cvt_pk_bf16_f32 v72, v66, v67
	v_lshlrev_b32_e32 v66, 16, v79
	v_mul_f32_e32 v73, 0xbfb8aa3b, v66
	v_exp_f32_e32 v73, v73
	v_and_b32_e32 v67, 0xffff0000, v79
	v_add_f32_e32 v73, 1.0, v73
	v_rcp_f32_e32 v76, v73
	v_mul_f32_e32 v73, 0xbfb8aa3b, v67
	v_exp_f32_e32 v73, v73
	s_nop 0
	v_add_f32_e32 v73, 1.0, v73
	v_rcp_f32_e32 v77, v73
	s_nop 0
	v_pk_mul_f32 v[66:67], v[76:77], v[66:67]
	s_nop 0
	v_pk_mul_f32 v[66:67], v[68:69], v[66:67]
	s_nop 0
	v_cvt_pk_bf16_f32 v73, v66, v67
	global_store_dwordx4 v[74:75], v[70:73], off offset:3328
	s_nop 1
	v_add_u32_e32 v66, 0x80, v142
	v_ashrrev_i32_e32 v67, 31, v66
	v_lshlrev_b64 v[68:69], 12, v[66:67]
	v_mad_i64_i32 v[66:67], s[30:31], v66, s77, v[144:145]
	v_lshl_add_u64 v[66:67], v[66:67], 0, v[140:141]
	v_add_co_u32_e32 v66, vcc, s34, v66
	s_nop 1
	v_addc_co_u32_e32 v67, vcc, 0, v67, vcc
	v_mov_b32_e32 v70, v196
	v_mov_b32_e32 v71, v197
	v_mov_b32_e32 v72, v198
	v_mov_b32_e32 v73, v199
	v_lshlrev_b32_e32 v74, 16, v70
	v_and_b32_e32 v75, 0xffff0000, v70
	v_mul_f32_e32 v70, 0xbfb8aa3b, v74
	v_exp_f32_e32 v70, v70
	s_nop 0
	v_add_f32_e32 v70, 1.0, v70
	v_rcp_f32_e32 v76, v70
	v_mul_f32_e32 v70, 0xbfb8aa3b, v75
	v_exp_f32_e32 v70, v70
	s_nop 0
	v_add_f32_e32 v70, 1.0, v70
	v_rcp_f32_e32 v77, v70
	v_lshlrev_b32_e32 v70, 16, v71
	v_and_b32_e32 v71, 0xffff0000, v71
	v_pk_mul_f32 v[74:75], v[76:77], v[74:75]
	s_nop 0
	v_pk_mul_f32 v[62:63], v[62:63], v[74:75]
	s_nop 0
	v_cvt_pk_bf16_f32 v62, v62, v63
	v_mul_f32_e32 v63, 0xbfb8aa3b, v70
	v_exp_f32_e32 v63, v63
	s_nop 0
	v_add_f32_e32 v63, 1.0, v63
	v_rcp_f32_e32 v74, v63
	v_mul_f32_e32 v63, 0xbfb8aa3b, v71
	v_exp_f32_e32 v63, v63
	s_nop 0
	v_add_f32_e32 v63, 1.0, v63
	v_rcp_f32_e32 v75, v63
	s_nop 0
	v_pk_mul_f32 v[70:71], v[74:75], v[70:71]
	s_nop 0
	v_pk_mul_f32 v[64:65], v[64:65], v[70:71]
	s_nop 0
	v_cvt_pk_bf16_f32 v63, v64, v65
	v_lshlrev_b32_e32 v64, 16, v72
	v_and_b32_e32 v65, 0xffff0000, v72
	v_mul_f32_e32 v70, 0xbfb8aa3b, v64
	v_mul_f32_e32 v71, 0xbfb8aa3b, v65
	v_exp_f32_e32 v70, v70
	v_exp_f32_e32 v71, v71
	v_add_f32_e32 v70, 1.0, v70
	v_add_f32_e32 v71, 1.0, v71
	v_rcp_f32_e32 v70, v70
	v_rcp_f32_e32 v71, v71
	s_nop 0
	v_pk_mul_f32 v[64:65], v[70:71], v[64:65]
	s_nop 0
	v_pk_mul_f32 v[58:59], v[58:59], v[64:65]
	s_nop 0
	v_cvt_pk_bf16_f32 v64, v58, v59
	v_lshlrev_b32_e32 v58, 16, v73
	v_mul_f32_e32 v65, 0xbfb8aa3b, v58
	v_exp_f32_e32 v65, v65
	v_and_b32_e32 v59, 0xffff0000, v73
	v_add_f32_e32 v65, 1.0, v65
	v_rcp_f32_e32 v70, v65
	v_mul_f32_e32 v65, 0xbfb8aa3b, v59
	v_exp_f32_e32 v65, v65
	s_nop 0
	v_add_f32_e32 v65, 1.0, v65
	v_rcp_f32_e32 v71, v65
	s_nop 0
	v_pk_mul_f32 v[58:59], v[70:71], v[58:59]
	s_nop 0
	v_pk_mul_f32 v[58:59], v[60:61], v[58:59]
	s_nop 0
	v_cvt_pk_bf16_f32 v65, v58, v59
	v_lshl_add_u64 v[58:59], s[64:65], 0, v[68:69]
	v_lshl_add_u64 v[58:59], v[58:59], 0, v[140:141]
	global_store_dwordx4 v[58:59], v[62:65], off offset:3072
	s_nop 1
	v_mov_b32_e32 v60, v206
	v_mov_b32_e32 v61, v207
	v_mov_b32_e32 v62, v208
	v_mov_b32_e32 v63, v209
	v_lshlrev_b32_e32 v64, 16, v60
	v_and_b32_e32 v65, 0xffff0000, v60
	v_mul_f32_e32 v60, 0xbfb8aa3b, v64
	v_exp_f32_e32 v60, v60
	s_nop 0
	v_add_f32_e32 v60, 1.0, v60
	v_rcp_f32_e32 v66, v60
	v_mul_f32_e32 v60, 0xbfb8aa3b, v65
	v_exp_f32_e32 v60, v60
	s_nop 0
	v_add_f32_e32 v60, 1.0, v60
	v_rcp_f32_e32 v67, v60
	v_lshlrev_b32_e32 v60, 16, v61
	v_and_b32_e32 v61, 0xffff0000, v61
	v_pk_mul_f32 v[64:65], v[66:67], v[64:65]
	s_nop 0
	v_pk_mul_f32 v[54:55], v[54:55], v[64:65]
	s_nop 0
	v_cvt_pk_bf16_f32 v54, v54, v55
	v_mul_f32_e32 v55, 0xbfb8aa3b, v60
	v_exp_f32_e32 v55, v55
	s_nop 0
	v_add_f32_e32 v55, 1.0, v55
	v_rcp_f32_e32 v64, v55
	v_mul_f32_e32 v55, 0xbfb8aa3b, v61
	v_exp_f32_e32 v55, v55
	s_nop 0
	v_add_f32_e32 v55, 1.0, v55
	v_rcp_f32_e32 v65, v55
	s_nop 0
	v_pk_mul_f32 v[60:61], v[64:65], v[60:61]
	s_nop 0
	v_pk_mul_f32 v[56:57], v[56:57], v[60:61]
	s_nop 0
	v_cvt_pk_bf16_f32 v55, v56, v57
	v_lshlrev_b32_e32 v56, 16, v62
	v_and_b32_e32 v57, 0xffff0000, v62
	v_mul_f32_e32 v60, 0xbfb8aa3b, v56
	v_mul_f32_e32 v61, 0xbfb8aa3b, v57
	v_exp_f32_e32 v60, v60
	v_exp_f32_e32 v61, v61
	v_add_f32_e32 v60, 1.0, v60
	v_add_f32_e32 v61, 1.0, v61
	v_rcp_f32_e32 v60, v60
	v_rcp_f32_e32 v61, v61
	s_nop 0
	v_pk_mul_f32 v[56:57], v[60:61], v[56:57]
	s_nop 0
	v_pk_mul_f32 v[50:51], v[50:51], v[56:57]
	s_nop 0
	v_cvt_pk_bf16_f32 v56, v50, v51
	v_lshlrev_b32_e32 v50, 16, v63
	v_mul_f32_e32 v57, 0xbfb8aa3b, v50
	v_exp_f32_e32 v57, v57
	v_and_b32_e32 v51, 0xffff0000, v63
	v_add_f32_e32 v57, 1.0, v57
	v_rcp_f32_e32 v60, v57
	v_mul_f32_e32 v57, 0xbfb8aa3b, v51
	v_exp_f32_e32 v57, v57
	s_nop 0
	v_add_f32_e32 v57, 1.0, v57
	v_rcp_f32_e32 v61, v57
	s_nop 0
	v_pk_mul_f32 v[50:51], v[60:61], v[50:51]
	s_nop 0
	v_pk_mul_f32 v[50:51], v[52:53], v[50:51]
	s_nop 0
	v_cvt_pk_bf16_f32 v57, v50, v51
	global_store_dwordx4 v[58:59], v[54:57], off offset:3328
	s_nop 1
	v_add_u32_e32 v50, 0x90, v142
	v_ashrrev_i32_e32 v51, 31, v50
	v_lshlrev_b64 v[52:53], 12, v[50:51]
	v_mad_i64_i32 v[50:51], s[30:31], v50, s77, v[144:145]
	v_lshl_add_u64 v[50:51], v[50:51], 0, v[140:141]
	v_add_co_u32_e32 v50, vcc, s34, v50
	s_nop 1
	v_addc_co_u32_e32 v51, vcc, 0, v51, vcc
	v_mov_b32_e32 v54, v210
	v_mov_b32_e32 v55, v211
	v_mov_b32_e32 v56, v212
	v_mov_b32_e32 v57, v213
	v_lshlrev_b32_e32 v58, 16, v54
	v_and_b32_e32 v59, 0xffff0000, v54
	v_mul_f32_e32 v54, 0xbfb8aa3b, v58
	v_exp_f32_e32 v54, v54
	s_nop 0
	v_add_f32_e32 v54, 1.0, v54
	v_rcp_f32_e32 v60, v54
	v_mul_f32_e32 v54, 0xbfb8aa3b, v59
	v_exp_f32_e32 v54, v54
	s_nop 0
	v_add_f32_e32 v54, 1.0, v54
	v_rcp_f32_e32 v61, v54
	v_lshlrev_b32_e32 v54, 16, v55
	v_and_b32_e32 v55, 0xffff0000, v55
	v_pk_mul_f32 v[58:59], v[60:61], v[58:59]
	s_nop 0
	v_pk_mul_f32 v[46:47], v[46:47], v[58:59]
	s_nop 0
	v_cvt_pk_bf16_f32 v46, v46, v47
	v_mul_f32_e32 v47, 0xbfb8aa3b, v54
	v_exp_f32_e32 v47, v47
	s_nop 0
	v_add_f32_e32 v47, 1.0, v47
	v_rcp_f32_e32 v58, v47
	v_mul_f32_e32 v47, 0xbfb8aa3b, v55
	v_exp_f32_e32 v47, v47
	s_nop 0
	v_add_f32_e32 v47, 1.0, v47
	v_rcp_f32_e32 v59, v47
	s_nop 0
	v_pk_mul_f32 v[54:55], v[58:59], v[54:55]
	s_nop 0
	v_pk_mul_f32 v[48:49], v[48:49], v[54:55]
	s_nop 0
	v_cvt_pk_bf16_f32 v47, v48, v49
	v_lshlrev_b32_e32 v48, 16, v56
	v_and_b32_e32 v49, 0xffff0000, v56
	v_mul_f32_e32 v54, 0xbfb8aa3b, v48
	v_mul_f32_e32 v55, 0xbfb8aa3b, v49
	v_exp_f32_e32 v54, v54
	v_exp_f32_e32 v55, v55
	v_add_f32_e32 v54, 1.0, v54
	v_add_f32_e32 v55, 1.0, v55
	v_rcp_f32_e32 v54, v54
	v_rcp_f32_e32 v55, v55
	s_nop 0
	v_pk_mul_f32 v[48:49], v[54:55], v[48:49]
	s_nop 0
	v_pk_mul_f32 v[42:43], v[42:43], v[48:49]
	s_nop 0
	v_cvt_pk_bf16_f32 v48, v42, v43
	v_lshlrev_b32_e32 v42, 16, v57
	v_mul_f32_e32 v49, 0xbfb8aa3b, v42
	v_exp_f32_e32 v49, v49
	v_and_b32_e32 v43, 0xffff0000, v57
	v_add_f32_e32 v49, 1.0, v49
	v_rcp_f32_e32 v54, v49
	v_mul_f32_e32 v49, 0xbfb8aa3b, v43
	v_exp_f32_e32 v49, v49
	s_nop 0
	v_add_f32_e32 v49, 1.0, v49
	v_rcp_f32_e32 v55, v49
	s_nop 0
	v_pk_mul_f32 v[42:43], v[54:55], v[42:43]
	s_nop 0
	v_pk_mul_f32 v[42:43], v[44:45], v[42:43]
	s_nop 0
	v_cvt_pk_bf16_f32 v49, v42, v43
	v_lshl_add_u64 v[42:43], s[64:65], 0, v[52:53]
	v_lshl_add_u64 v[42:43], v[42:43], 0, v[140:141]
	global_store_dwordx4 v[42:43], v[46:49], off offset:3072
	s_nop 1
	v_mov_b32_e32 v44, v214
	v_mov_b32_e32 v45, v215
	v_mov_b32_e32 v46, v216
	v_mov_b32_e32 v47, v217
	v_lshlrev_b32_e32 v48, 16, v44
	v_and_b32_e32 v49, 0xffff0000, v44
	v_mul_f32_e32 v44, 0xbfb8aa3b, v48
	v_exp_f32_e32 v44, v44
	s_nop 0
	v_add_f32_e32 v44, 1.0, v44
	v_rcp_f32_e32 v50, v44
	v_mul_f32_e32 v44, 0xbfb8aa3b, v49
	v_exp_f32_e32 v44, v44
	s_nop 0
	v_add_f32_e32 v44, 1.0, v44
	v_rcp_f32_e32 v51, v44
	v_lshlrev_b32_e32 v44, 16, v45
	v_and_b32_e32 v45, 0xffff0000, v45
	v_pk_mul_f32 v[48:49], v[50:51], v[48:49]
	s_nop 0
	v_pk_mul_f32 v[38:39], v[38:39], v[48:49]
	s_nop 0
	v_cvt_pk_bf16_f32 v38, v38, v39
	v_mul_f32_e32 v39, 0xbfb8aa3b, v44
	v_exp_f32_e32 v39, v39
	s_nop 0
	v_add_f32_e32 v39, 1.0, v39
	v_rcp_f32_e32 v48, v39
	v_mul_f32_e32 v39, 0xbfb8aa3b, v45
	v_exp_f32_e32 v39, v39
	s_nop 0
	v_add_f32_e32 v39, 1.0, v39
	v_rcp_f32_e32 v49, v39
	s_nop 0
	v_pk_mul_f32 v[44:45], v[48:49], v[44:45]
	s_nop 0
	v_pk_mul_f32 v[40:41], v[40:41], v[44:45]
	s_nop 0
	v_cvt_pk_bf16_f32 v39, v40, v41
	v_lshlrev_b32_e32 v40, 16, v46
	v_and_b32_e32 v41, 0xffff0000, v46
	v_mul_f32_e32 v44, 0xbfb8aa3b, v40
	v_mul_f32_e32 v45, 0xbfb8aa3b, v41
	v_exp_f32_e32 v44, v44
	v_exp_f32_e32 v45, v45
	v_add_f32_e32 v44, 1.0, v44
	v_add_f32_e32 v45, 1.0, v45
	v_rcp_f32_e32 v44, v44
	v_rcp_f32_e32 v45, v45
	s_nop 0
	v_pk_mul_f32 v[40:41], v[44:45], v[40:41]
	s_nop 0
	v_pk_mul_f32 v[34:35], v[34:35], v[40:41]
	s_nop 0
	v_cvt_pk_bf16_f32 v40, v34, v35
	v_lshlrev_b32_e32 v34, 16, v47
	v_mul_f32_e32 v41, 0xbfb8aa3b, v34
	v_exp_f32_e32 v41, v41
	v_and_b32_e32 v35, 0xffff0000, v47
	v_add_f32_e32 v41, 1.0, v41
	v_rcp_f32_e32 v44, v41
	v_mul_f32_e32 v41, 0xbfb8aa3b, v35
	v_exp_f32_e32 v41, v41
	s_nop 0
	v_add_f32_e32 v41, 1.0, v41
	v_rcp_f32_e32 v45, v41
	s_nop 0
	v_pk_mul_f32 v[34:35], v[44:45], v[34:35]
	s_nop 0
	v_pk_mul_f32 v[34:35], v[36:37], v[34:35]
	s_nop 0
	v_cvt_pk_bf16_f32 v41, v34, v35
	global_store_dwordx4 v[42:43], v[38:41], off offset:3328
	s_nop 1
	v_add_u32_e32 v34, 0xa0, v142
	v_ashrrev_i32_e32 v35, 31, v34
	v_lshlrev_b64 v[36:37], 12, v[34:35]
	v_mad_i64_i32 v[34:35], s[30:31], v34, s77, v[144:145]
	v_lshl_add_u64 v[34:35], v[34:35], 0, v[140:141]
	v_add_co_u32_e32 v34, vcc, s34, v34
	s_nop 1
	v_addc_co_u32_e32 v35, vcc, 0, v35, vcc
	v_mov_b32_e32 v38, v218
	v_mov_b32_e32 v39, v219
	v_mov_b32_e32 v40, v220
	v_mov_b32_e32 v41, v221
	v_lshlrev_b32_e32 v42, 16, v38
	v_and_b32_e32 v43, 0xffff0000, v38
	v_mul_f32_e32 v38, 0xbfb8aa3b, v42
	v_exp_f32_e32 v38, v38
	s_nop 0
	v_add_f32_e32 v38, 1.0, v38
	v_rcp_f32_e32 v44, v38
	v_mul_f32_e32 v38, 0xbfb8aa3b, v43
	v_exp_f32_e32 v38, v38
	s_nop 0
	v_add_f32_e32 v38, 1.0, v38
	v_rcp_f32_e32 v45, v38
	v_lshlrev_b32_e32 v38, 16, v39
	v_and_b32_e32 v39, 0xffff0000, v39
	v_pk_mul_f32 v[42:43], v[44:45], v[42:43]
	s_nop 0
	v_pk_mul_f32 v[30:31], v[30:31], v[42:43]
	s_nop 0
	v_cvt_pk_bf16_f32 v30, v30, v31
	v_mul_f32_e32 v31, 0xbfb8aa3b, v38
	v_exp_f32_e32 v31, v31
	s_nop 0
	v_add_f32_e32 v31, 1.0, v31
	v_rcp_f32_e32 v42, v31
	v_mul_f32_e32 v31, 0xbfb8aa3b, v39
	v_exp_f32_e32 v31, v31
	s_nop 0
	v_add_f32_e32 v31, 1.0, v31
	v_rcp_f32_e32 v43, v31
	s_nop 0
	v_pk_mul_f32 v[38:39], v[42:43], v[38:39]
	s_nop 0
	v_pk_mul_f32 v[32:33], v[32:33], v[38:39]
	s_nop 0
	v_cvt_pk_bf16_f32 v31, v32, v33
	v_lshlrev_b32_e32 v32, 16, v40
	v_and_b32_e32 v33, 0xffff0000, v40
	v_mul_f32_e32 v38, 0xbfb8aa3b, v32
	v_mul_f32_e32 v39, 0xbfb8aa3b, v33
	v_exp_f32_e32 v38, v38
	v_exp_f32_e32 v39, v39
	v_add_f32_e32 v38, 1.0, v38
	v_add_f32_e32 v39, 1.0, v39
	v_rcp_f32_e32 v38, v38
	v_rcp_f32_e32 v39, v39
	s_nop 0
	v_pk_mul_f32 v[32:33], v[38:39], v[32:33]
	s_nop 0
	v_pk_mul_f32 v[26:27], v[26:27], v[32:33]
	s_nop 0
	v_cvt_pk_bf16_f32 v32, v26, v27
	v_lshlrev_b32_e32 v26, 16, v41
	v_mul_f32_e32 v33, 0xbfb8aa3b, v26
	v_exp_f32_e32 v33, v33
	v_and_b32_e32 v27, 0xffff0000, v41
	v_add_f32_e32 v33, 1.0, v33
	v_rcp_f32_e32 v38, v33
	v_mul_f32_e32 v33, 0xbfb8aa3b, v27
	v_exp_f32_e32 v33, v33
	s_nop 0
	v_add_f32_e32 v33, 1.0, v33
	v_rcp_f32_e32 v39, v33
	s_nop 0
	v_pk_mul_f32 v[26:27], v[38:39], v[26:27]
	s_nop 0
	v_pk_mul_f32 v[26:27], v[28:29], v[26:27]
	s_nop 0
	v_cvt_pk_bf16_f32 v33, v26, v27
	v_lshl_add_u64 v[26:27], s[64:65], 0, v[36:37]
	v_lshl_add_u64 v[26:27], v[26:27], 0, v[140:141]
	global_store_dwordx4 v[26:27], v[30:33], off offset:3072
	s_nop 1
	v_mov_b32_e32 v28, v222
	v_mov_b32_e32 v29, v223
	v_mov_b32_e32 v30, v224
	v_mov_b32_e32 v31, v225
	v_lshlrev_b32_e32 v32, 16, v28
	v_and_b32_e32 v33, 0xffff0000, v28
	v_mul_f32_e32 v28, 0xbfb8aa3b, v32
	v_exp_f32_e32 v28, v28
	s_nop 0
	v_add_f32_e32 v28, 1.0, v28
	v_rcp_f32_e32 v34, v28
	v_mul_f32_e32 v28, 0xbfb8aa3b, v33
	v_exp_f32_e32 v28, v28
	s_nop 0
	v_add_f32_e32 v28, 1.0, v28
	v_rcp_f32_e32 v35, v28
	v_lshlrev_b32_e32 v28, 16, v29
	v_and_b32_e32 v29, 0xffff0000, v29
	v_pk_mul_f32 v[32:33], v[34:35], v[32:33]
	s_nop 0
	v_pk_mul_f32 v[22:23], v[22:23], v[32:33]
	s_nop 0
	v_cvt_pk_bf16_f32 v22, v22, v23
	v_mul_f32_e32 v23, 0xbfb8aa3b, v28
	v_exp_f32_e32 v23, v23
	s_nop 0
	v_add_f32_e32 v23, 1.0, v23
	v_rcp_f32_e32 v32, v23
	v_mul_f32_e32 v23, 0xbfb8aa3b, v29
	v_exp_f32_e32 v23, v23
	s_nop 0
	v_add_f32_e32 v23, 1.0, v23
	v_rcp_f32_e32 v33, v23
	s_nop 0
	v_pk_mul_f32 v[28:29], v[32:33], v[28:29]
	s_nop 0
	v_pk_mul_f32 v[24:25], v[24:25], v[28:29]
	s_nop 0
	v_cvt_pk_bf16_f32 v23, v24, v25
	v_lshlrev_b32_e32 v24, 16, v30
	v_and_b32_e32 v25, 0xffff0000, v30
	v_mul_f32_e32 v28, 0xbfb8aa3b, v24
	v_mul_f32_e32 v29, 0xbfb8aa3b, v25
	v_exp_f32_e32 v28, v28
	v_exp_f32_e32 v29, v29
	v_add_f32_e32 v28, 1.0, v28
	v_add_f32_e32 v29, 1.0, v29
	v_rcp_f32_e32 v28, v28
	v_rcp_f32_e32 v29, v29
	s_nop 0
	v_pk_mul_f32 v[24:25], v[28:29], v[24:25]
	s_nop 0
	v_pk_mul_f32 v[18:19], v[18:19], v[24:25]
	s_nop 0
	v_cvt_pk_bf16_f32 v24, v18, v19
	v_lshlrev_b32_e32 v18, 16, v31
	v_mul_f32_e32 v25, 0xbfb8aa3b, v18
	v_exp_f32_e32 v25, v25
	v_and_b32_e32 v19, 0xffff0000, v31
	v_add_f32_e32 v25, 1.0, v25
	v_rcp_f32_e32 v28, v25
	v_mul_f32_e32 v25, 0xbfb8aa3b, v19
	v_exp_f32_e32 v25, v25
	s_nop 0
	v_add_f32_e32 v25, 1.0, v25
	v_rcp_f32_e32 v29, v25
	s_nop 0
	v_pk_mul_f32 v[18:19], v[28:29], v[18:19]
	s_nop 0
	v_pk_mul_f32 v[18:19], v[20:21], v[18:19]
	s_nop 0
	v_cvt_pk_bf16_f32 v25, v18, v19
	global_store_dwordx4 v[26:27], v[22:25], off offset:3328
	s_nop 1
	v_add_u32_e32 v18, 0xb0, v142
	v_ashrrev_i32_e32 v19, 31, v18
	v_lshlrev_b64 v[20:21], 12, v[18:19]
	v_mad_i64_i32 v[18:19], s[30:31], v18, s77, v[144:145]
	v_lshl_add_u64 v[18:19], v[18:19], 0, v[140:141]
	v_add_co_u32_e32 v18, vcc, s34, v18
	s_nop 1
	v_addc_co_u32_e32 v19, vcc, 0, v19, vcc
	v_mov_b32_e32 v22, v226
	v_mov_b32_e32 v23, v227
	v_mov_b32_e32 v24, v228
	v_mov_b32_e32 v25, v229
	v_lshlrev_b32_e32 v26, 16, v22
	v_and_b32_e32 v27, 0xffff0000, v22
	v_mul_f32_e32 v22, 0xbfb8aa3b, v26
	v_exp_f32_e32 v22, v22
	s_nop 0
	v_add_f32_e32 v22, 1.0, v22
	v_rcp_f32_e32 v28, v22
	v_mul_f32_e32 v22, 0xbfb8aa3b, v27
	v_exp_f32_e32 v22, v22
	s_nop 0
	v_add_f32_e32 v22, 1.0, v22
	v_rcp_f32_e32 v29, v22
	v_lshlrev_b32_e32 v22, 16, v23
	v_and_b32_e32 v23, 0xffff0000, v23
	v_pk_mul_f32 v[26:27], v[28:29], v[26:27]
	s_nop 0
	v_pk_mul_f32 v[14:15], v[14:15], v[26:27]
	s_nop 0
	v_cvt_pk_bf16_f32 v14, v14, v15
	v_mul_f32_e32 v15, 0xbfb8aa3b, v22
	v_exp_f32_e32 v15, v15
	s_nop 0
	v_add_f32_e32 v15, 1.0, v15
	v_rcp_f32_e32 v26, v15
	v_mul_f32_e32 v15, 0xbfb8aa3b, v23
	v_exp_f32_e32 v15, v15
	s_nop 0
	v_add_f32_e32 v15, 1.0, v15
	v_rcp_f32_e32 v27, v15
	s_nop 0
	v_pk_mul_f32 v[22:23], v[26:27], v[22:23]
	s_nop 0
	v_pk_mul_f32 v[16:17], v[16:17], v[22:23]
	s_nop 0
	v_cvt_pk_bf16_f32 v15, v16, v17
	v_lshlrev_b32_e32 v16, 16, v24
	v_and_b32_e32 v17, 0xffff0000, v24
	v_mul_f32_e32 v22, 0xbfb8aa3b, v16
	v_mul_f32_e32 v23, 0xbfb8aa3b, v17
	v_exp_f32_e32 v22, v22
	v_exp_f32_e32 v23, v23
	v_add_f32_e32 v22, 1.0, v22
	v_add_f32_e32 v23, 1.0, v23
	v_rcp_f32_e32 v22, v22
	v_rcp_f32_e32 v23, v23
	s_nop 0
	v_pk_mul_f32 v[16:17], v[22:23], v[16:17]
	s_nop 0
	v_pk_mul_f32 v[10:11], v[10:11], v[16:17]
	s_nop 0
	v_cvt_pk_bf16_f32 v16, v10, v11
	v_lshlrev_b32_e32 v10, 16, v25
	v_mul_f32_e32 v17, 0xbfb8aa3b, v10
	v_exp_f32_e32 v17, v17
	v_and_b32_e32 v11, 0xffff0000, v25
	v_add_f32_e32 v17, 1.0, v17
	v_rcp_f32_e32 v22, v17
	v_mul_f32_e32 v17, 0xbfb8aa3b, v11
	v_exp_f32_e32 v17, v17
	s_nop 0
	v_add_f32_e32 v17, 1.0, v17
	v_rcp_f32_e32 v23, v17
	s_nop 0
	v_pk_mul_f32 v[10:11], v[22:23], v[10:11]
	s_nop 0
	v_pk_mul_f32 v[10:11], v[12:13], v[10:11]
	s_nop 0
	v_cvt_pk_bf16_f32 v17, v10, v11
	v_lshl_add_u64 v[10:11], s[64:65], 0, v[20:21]
	v_lshl_add_u64 v[10:11], v[10:11], 0, v[140:141]
	global_store_dwordx4 v[10:11], v[14:17], off offset:3072
	s_nop 1
	v_mov_b32_e32 v12, v230
	v_mov_b32_e32 v13, v231
	v_mov_b32_e32 v14, v232
	v_mov_b32_e32 v15, v233
	v_lshlrev_b32_e32 v16, 16, v12
	v_and_b32_e32 v17, 0xffff0000, v12
	v_mul_f32_e32 v12, 0xbfb8aa3b, v16
	v_exp_f32_e32 v12, v12
	s_nop 0
	v_add_f32_e32 v12, 1.0, v12
	v_rcp_f32_e32 v18, v12
	v_mul_f32_e32 v12, 0xbfb8aa3b, v17
	v_exp_f32_e32 v12, v12
	s_nop 0
	v_add_f32_e32 v12, 1.0, v12
	v_rcp_f32_e32 v19, v12
	v_lshlrev_b32_e32 v12, 16, v13
	v_and_b32_e32 v13, 0xffff0000, v13
	v_pk_mul_f32 v[16:17], v[18:19], v[16:17]
	s_nop 0
	v_pk_mul_f32 v[6:7], v[6:7], v[16:17]
	s_nop 0
	v_cvt_pk_bf16_f32 v6, v6, v7
	v_mul_f32_e32 v7, 0xbfb8aa3b, v12
	v_exp_f32_e32 v7, v7
	s_nop 0
	v_add_f32_e32 v7, 1.0, v7
	v_rcp_f32_e32 v16, v7
	v_mul_f32_e32 v7, 0xbfb8aa3b, v13
	v_exp_f32_e32 v7, v7
	s_nop 0
	v_add_f32_e32 v7, 1.0, v7
	v_rcp_f32_e32 v17, v7
	s_nop 0
	v_pk_mul_f32 v[12:13], v[16:17], v[12:13]
	s_nop 0
	v_pk_mul_f32 v[8:9], v[8:9], v[12:13]
	s_nop 0
	v_cvt_pk_bf16_f32 v7, v8, v9
	v_lshlrev_b32_e32 v8, 16, v14
	v_and_b32_e32 v9, 0xffff0000, v14
	v_mul_f32_e32 v12, 0xbfb8aa3b, v8
	v_mul_f32_e32 v13, 0xbfb8aa3b, v9
	v_exp_f32_e32 v12, v12
	v_exp_f32_e32 v13, v13
	v_add_f32_e32 v12, 1.0, v12
	v_add_f32_e32 v13, 1.0, v13
	v_rcp_f32_e32 v12, v12
	v_rcp_f32_e32 v13, v13
	s_nop 0
	v_pk_mul_f32 v[8:9], v[12:13], v[8:9]
	s_nop 0
	v_pk_mul_f32 v[2:3], v[2:3], v[8:9]
	s_nop 0
	v_cvt_pk_bf16_f32 v8, v2, v3
	v_lshlrev_b32_e32 v2, 16, v15
	v_mul_f32_e32 v9, 0xbfb8aa3b, v2
	v_exp_f32_e32 v9, v9
	v_and_b32_e32 v3, 0xffff0000, v15
	v_add_f32_e32 v9, 1.0, v9
	v_rcp_f32_e32 v12, v9
	v_mul_f32_e32 v9, 0xbfb8aa3b, v3
	v_exp_f32_e32 v9, v9
	s_nop 0
	v_add_f32_e32 v9, 1.0, v9
	v_rcp_f32_e32 v13, v9
	s_nop 0
	v_pk_mul_f32 v[2:3], v[12:13], v[2:3]
	s_nop 0
	v_pk_mul_f32 v[2:3], v[4:5], v[2:3]
	s_nop 0
	v_cvt_pk_bf16_f32 v9, v2, v3
	global_store_dwordx4 v[10:11], v[6:9], off offset:3328
	s_nop 1
	s_and_b64 vcc, exec, s[36:37]
	s_mov_b32 s62, s80
	s_mov_b32 s81, s18
	s_mov_b64 s[38:39], s[40:41]
	s_mov_b64 s[30:31], s[0:1]
	s_cbranch_vccnz .LBB0_739

.LBB0_748:
	s_lshl_b32 s38, s87, 8
	v_mov_b32_e32 v140, v150
	v_mov_b32_e32 v142, v141
	s_lshl_b32 s30, s87, 10
	s_lshl_b32 s31, s88, 8
	s_and_b32 s39, s38, 0x100
	s_and_b32 s30, s30, 0xfffff800
	s_or_b32 s39, s39, s22
	s_add_i32 s31, s84, s31
	v_lshl_add_u32 v142, v142, 3, s39
	s_add_i32 s31, s31, s30
	s_and_b32 s30, s38, 0xfffffe00
	v_add_u32_e32 v146, s31, v140
	v_ashrrev_i32_e32 v143, 31, v142
	s_ashr_i32 s31, s30, 31
	v_mov_b64_e32 v[148:149], s[24:25]
	v_mad_i64_i32 v[154:155], s[38:39], v146, s77, v[148:149]
	v_lshlrev_b64 v[144:145], 1, v[142:143]
	s_lshl_b64 s[30:31], s[30:31], 2
	v_lshl_add_u64 v[162:163], v[154:155], 0, v[144:145]
	s_add_u32 s30, s66, s30
	s_addc_u32 s31, s67, s31
	v_add_co_u32_e32 v166, vcc, s34, v162
	v_lshl_add_u64 v[142:143], v[142:143], 2, s[30:31]
	s_nop 0
	v_addc_co_u32_e32 v167, vcc, 0, v163, vcc
	v_mov_b32_e32 v194, v166
	v_mov_b32_e32 v195, v167
	global_load_dwordx4 v[206:209], v[166:167], off offset:1024
	global_load_dwordx4 v[210:213], v[166:167], off offset:1280
	v_add_co_u32_e32 v246, vcc, 0x28000, v166
	s_nop 1
	v_addc_co_u32_e32 v247, vcc, 0, v167, vcc
	global_load_dwordx4 v[214:217], v[246:247], off offset:1024
	global_load_dwordx4 v[218:221], v[246:247], off offset:1280
	v_add_co_u32_e32 v246, vcc, 0x50000, v166
	s_nop 1
	v_addc_co_u32_e32 v247, vcc, 0, v167, vcc
	global_load_dwordx4 v[222:225], v[246:247], off offset:1024
	global_load_dwordx4 v[226:229], v[246:247], off offset:1280
	v_add_co_u32_e32 v246, vcc, 0x78000, v166
	s_nop 1
	v_addc_co_u32_e32 v247, vcc, 0, v167, vcc
	global_load_dwordx4 v[230:233], v[246:247], off offset:1024
	global_load_dwordx4 v[196:199], v[246:247], off offset:1280
	global_load_dwordx4 v[178:181], v[142:143], off
	global_load_dwordx4 v[182:185], v[142:143], off offset:16
	global_load_dwordx4 v[186:189], v[142:143], off offset:512
	global_load_dwordx4 v[190:193], v[142:143], off offset:528
	v_and_b32_e32 v140, 1, v140
	v_cmp_eq_u32_e32 vcc, 0, v140
	v_ashrrev_i32_e32 v147, 31, v146
	v_lshlrev_b64 v[168:169], 12, v[146:147]
	v_cndmask_b32_e32 v140, v240, v241, vcc
	v_lshl_add_u64 v[168:169], s[64:65], 0, v[168:169]
	s_waitcnt vmcnt(0)
	v_mov_b32_e32 v162, v206
	v_mov_b32_e32 v163, v207
	v_mov_b32_e32 v164, v208
	v_mov_b32_e32 v165, v209
	v_mov_b32_e32 v154, v182
	v_mov_b32_e32 v155, v183
	v_mov_b32_e32 v156, v184
	v_mov_b32_e32 v157, v185
	v_mov_b32_e32 v158, v178
	v_mov_b32_e32 v159, v179
	v_mov_b32_e32 v160, v180
	v_mov_b32_e32 v161, v181
	v_pk_fma_f32 v[128:129], v[156:157], v[140:141], v[128:129] op_sel_hi:[1,0,1]
	v_pk_fma_f32 v[124:125], v[160:161], v[140:141], v[124:125] op_sel_hi:[1,0,1]
	v_pk_fma_f32 v[122:123], v[158:159], v[140:141], v[122:123] op_sel_hi:[1,0,1]
	v_pk_fma_f32 v[126:127], v[154:155], v[140:141], v[126:127] op_sel_hi:[1,0,1]
	s_waitcnt lgkmcnt(0)
	v_lshlrev_b32_e32 v154, 16, v162
	v_and_b32_e32 v155, 0xffff0000, v162
	v_lshlrev_b32_e32 v156, 16, v163
	v_and_b32_e32 v157, 0xffff0000, v163
	v_lshlrev_b32_e32 v158, 16, v164
	v_and_b32_e32 v159, 0xffff0000, v164
	v_lshlrev_b32_e32 v160, 16, v165
	v_and_b32_e32 v161, 0xffff0000, v165
	v_mul_f32_e32 v147, 0xbfb8aa3b, v154
	v_mul_f32_e32 v153, 0xbfb8aa3b, v155
	v_mul_f32_e32 v162, 0xbfb8aa3b, v156
	v_mul_f32_e32 v163, 0xbfb8aa3b, v157
	v_mul_f32_e32 v164, 0xbfb8aa3b, v158
	v_mul_f32_e32 v165, 0xbfb8aa3b, v159
	v_mul_f32_e32 v170, 0xbfb8aa3b, v160
	v_mul_f32_e32 v171, 0xbfb8aa3b, v161
	v_exp_f32_e32 v147, v147
	v_exp_f32_e32 v153, v153
	v_exp_f32_e32 v162, v162
	v_exp_f32_e32 v163, v163
	v_exp_f32_e32 v164, v164
	v_exp_f32_e32 v165, v165
	v_exp_f32_e32 v170, v170
	v_exp_f32_e32 v171, v171
	v_add_f32_e32 v147, 1.0, v147
	v_add_f32_e32 v153, 1.0, v153
	v_add_f32_e32 v172, 1.0, v162
	v_add_f32_e32 v173, 1.0, v163
	v_add_f32_e32 v174, 1.0, v164
	v_add_f32_e32 v175, 1.0, v165
	v_add_f32_e32 v176, 1.0, v170
	v_add_f32_e32 v177, 1.0, v171
	v_rcp_f32_e32 v162, v147
	v_rcp_f32_e32 v163, v153
	v_rcp_f32_e32 v164, v172
	v_rcp_f32_e32 v165, v173
	v_rcp_f32_e32 v170, v174
	v_rcp_f32_e32 v171, v175
	v_rcp_f32_e32 v172, v176
	v_rcp_f32_e32 v173, v177
	v_pk_mul_f32 v[154:155], v[162:163], v[154:155]
	v_pk_mul_f32 v[156:157], v[164:165], v[156:157]
	v_pk_mul_f32 v[158:159], v[170:171], v[158:159]
	v_pk_mul_f32 v[160:161], v[172:173], v[160:161]
	v_pk_mul_f32 v[122:123], v[154:155], v[122:123]
	v_pk_mul_f32 v[154:155], v[156:157], v[124:125]
	v_pk_mul_f32 v[126:127], v[158:159], v[126:127]
	v_pk_mul_f32 v[128:129], v[160:161], v[128:129]
	v_cvt_pk_bf16_f32 v124, v122, v123
	v_cvt_pk_bf16_f32 v125, v154, v155
	v_cvt_pk_bf16_f32 v126, v126, v127
	v_cvt_pk_bf16_f32 v127, v128, v129
	v_lshl_add_u64 v[122:123], v[168:169], 0, v[144:145]
	global_store_dwordx4 v[122:123], v[124:127], off offset:3072
	s_nop 1
	v_mov_b32_e32 v124, v210
	v_mov_b32_e32 v125, v211
	v_mov_b32_e32 v126, v212
	v_mov_b32_e32 v127, v213
	s_nop 0
	v_mov_b32_e32 v154, v190
	v_mov_b32_e32 v155, v191
	v_mov_b32_e32 v156, v192
	v_mov_b32_e32 v157, v193
	v_mov_b32_e32 v158, v186
	v_mov_b32_e32 v159, v187
	v_mov_b32_e32 v160, v188
	v_mov_b32_e32 v161, v189
	v_pk_fma_f32 v[128:129], v[140:141], v[158:159], v[118:119] op_sel_hi:[0,1,1]
	v_pk_fma_f32 v[118:119], v[140:141], v[156:157], v[116:117] op_sel_hi:[0,1,1]
	v_pk_fma_f32 v[116:117], v[140:141], v[154:155], v[114:115] op_sel_hi:[0,1,1]
	s_waitcnt lgkmcnt(0)
	v_lshlrev_b32_e32 v114, 16, v124
	v_and_b32_e32 v115, 0xffff0000, v124
	v_mul_f32_e32 v124, 0xbfb8aa3b, v114
	v_exp_f32_e32 v124, v124
	v_pk_fma_f32 v[120:121], v[140:141], v[160:161], v[120:121] op_sel_hi:[0,1,1]
	v_add_f32_e32 v124, 1.0, v124
	v_rcp_f32_e32 v154, v124
	v_mul_f32_e32 v124, 0xbfb8aa3b, v115
	v_exp_f32_e32 v124, v124
	s_nop 0
	v_add_f32_e32 v124, 1.0, v124
	v_rcp_f32_e32 v155, v124
	v_lshlrev_b32_e32 v124, 16, v125
	v_and_b32_e32 v125, 0xffff0000, v125
	v_pk_mul_f32 v[114:115], v[154:155], v[114:115]
	s_nop 0
	v_pk_mul_f32 v[114:115], v[128:129], v[114:115]
	s_nop 0
	v_cvt_pk_bf16_f32 v114, v114, v115
	v_mul_f32_e32 v115, 0xbfb8aa3b, v124
	v_exp_f32_e32 v115, v115
	s_nop 0
	v_add_f32_e32 v115, 1.0, v115
	v_rcp_f32_e32 v128, v115
	v_mul_f32_e32 v115, 0xbfb8aa3b, v125
	v_exp_f32_e32 v115, v115
	s_nop 0
	v_add_f32_e32 v115, 1.0, v115
	v_rcp_f32_e32 v129, v115
	s_nop 0
	v_pk_mul_f32 v[124:125], v[128:129], v[124:125]
	s_nop 0
	v_pk_mul_f32 v[120:121], v[120:121], v[124:125]
	s_nop 0
	v_cvt_pk_bf16_f32 v115, v120, v121
	v_lshlrev_b32_e32 v120, 16, v126
	v_and_b32_e32 v121, 0xffff0000, v126
	v_mul_f32_e32 v124, 0xbfb8aa3b, v120
	v_mul_f32_e32 v125, 0xbfb8aa3b, v121
	v_exp_f32_e32 v124, v124
	v_exp_f32_e32 v125, v125
	v_add_f32_e32 v124, 1.0, v124
	v_add_f32_e32 v125, 1.0, v125
	v_rcp_f32_e32 v124, v124
	v_rcp_f32_e32 v125, v125
	s_nop 0
	v_pk_mul_f32 v[120:121], v[124:125], v[120:121]
	s_nop 0
	v_pk_mul_f32 v[116:117], v[116:117], v[120:121]
	v_lshlrev_b32_e32 v120, 16, v127
	v_cvt_pk_bf16_f32 v116, v116, v117
	v_mul_f32_e32 v117, 0xbfb8aa3b, v120
	v_exp_f32_e32 v117, v117
	v_and_b32_e32 v121, 0xffff0000, v127
	v_add_f32_e32 v117, 1.0, v117
	v_rcp_f32_e32 v124, v117
	v_mul_f32_e32 v117, 0xbfb8aa3b, v121
	v_exp_f32_e32 v117, v117
	s_nop 0
	v_add_f32_e32 v117, 1.0, v117
	v_rcp_f32_e32 v125, v117
	s_nop 0
	v_pk_mul_f32 v[120:121], v[124:125], v[120:121]
	s_nop 0
	v_pk_mul_f32 v[118:119], v[118:119], v[120:121]
	s_nop 0
	v_cvt_pk_bf16_f32 v117, v118, v119
	global_store_dwordx4 v[122:123], v[114:117], off offset:3328
	s_nop 1
	s_nop 1
	v_add_u32_e32 v114, 16, v146
	v_ashrrev_i32_e32 v115, 31, v114
	v_lshlrev_b64 v[116:117], 12, v[114:115]
	v_mad_i64_i32 v[114:115], s[30:31], v114, s77, v[148:149]
	v_lshl_add_u64 v[114:115], v[114:115], 0, v[144:145]
	v_add_co_u32_e32 v114, vcc, s34, v114
	s_nop 1
	v_addc_co_u32_e32 v115, vcc, 0, v115, vcc
	v_mov_b32_e32 v118, v214
	v_mov_b32_e32 v119, v215
	v_mov_b32_e32 v120, v216
	v_mov_b32_e32 v121, v217
	v_mov_b32_e32 v122, v182
	v_mov_b32_e32 v123, v183
	v_mov_b32_e32 v124, v184
	v_mov_b32_e32 v125, v185
	v_mov_b32_e32 v126, v178
	v_mov_b32_e32 v127, v179
	v_mov_b32_e32 v128, v180
	v_mov_b32_e32 v129, v181
	v_pk_fma_f32 v[124:125], v[140:141], v[124:125], v[108:109] op_sel_hi:[0,1,1]
	v_pk_fma_f32 v[108:109], v[140:141], v[122:123], v[106:107] op_sel_hi:[0,1,1]
	s_waitcnt lgkmcnt(0)
	v_lshlrev_b32_e32 v106, 16, v118
	v_and_b32_e32 v107, 0xffff0000, v118
	v_mul_f32_e32 v118, 0xbfb8aa3b, v106
	v_exp_f32_e32 v118, v118
	v_pk_fma_f32 v[110:111], v[140:141], v[126:127], v[110:111] op_sel_hi:[0,1,1]
	v_pk_fma_f32 v[112:113], v[140:141], v[128:129], v[112:113] op_sel_hi:[0,1,1]
	v_add_f32_e32 v118, 1.0, v118
	v_rcp_f32_e32 v122, v118
	v_mul_f32_e32 v118, 0xbfb8aa3b, v107
	v_exp_f32_e32 v118, v118
	s_nop 0
	v_add_f32_e32 v118, 1.0, v118
	v_rcp_f32_e32 v123, v118
	s_nop 0
	v_pk_mul_f32 v[106:107], v[122:123], v[106:107]
	s_nop 0
	v_pk_mul_f32 v[106:107], v[110:111], v[106:107]
	v_lshlrev_b32_e32 v110, 16, v119
	v_cvt_pk_bf16_f32 v106, v106, v107
	v_mul_f32_e32 v107, 0xbfb8aa3b, v110
	v_exp_f32_e32 v107, v107
	v_and_b32_e32 v111, 0xffff0000, v119
	v_add_f32_e32 v107, 1.0, v107
	v_rcp_f32_e32 v118, v107
	v_mul_f32_e32 v107, 0xbfb8aa3b, v111
	v_exp_f32_e32 v107, v107
	s_nop 0
	v_add_f32_e32 v107, 1.0, v107
	v_rcp_f32_e32 v119, v107
	s_nop 0
	v_pk_mul_f32 v[110:111], v[118:119], v[110:111]
	s_nop 0
	v_pk_mul_f32 v[110:111], v[112:113], v[110:111]
	s_nop 0
	v_cvt_pk_bf16_f32 v107, v110, v111
	v_lshlrev_b32_e32 v110, 16, v120
	v_and_b32_e32 v111, 0xffff0000, v120
	v_mul_f32_e32 v112, 0xbfb8aa3b, v110
	v_mul_f32_e32 v113, 0xbfb8aa3b, v111
	v_exp_f32_e32 v112, v112
	v_exp_f32_e32 v113, v113
	v_add_f32_e32 v112, 1.0, v112
	v_add_f32_e32 v113, 1.0, v113
	v_rcp_f32_e32 v112, v112
	v_rcp_f32_e32 v113, v113
	s_nop 0
	v_pk_mul_f32 v[110:111], v[112:113], v[110:111]
	s_nop 0
	v_pk_mul_f32 v[108:109], v[108:109], v[110:111]
	v_lshlrev_b32_e32 v110, 16, v121
	v_cvt_pk_bf16_f32 v108, v108, v109
	v_mul_f32_e32 v109, 0xbfb8aa3b, v110
	v_exp_f32_e32 v109, v109
	v_and_b32_e32 v111, 0xffff0000, v121
	v_add_f32_e32 v109, 1.0, v109
	v_rcp_f32_e32 v112, v109
	v_mul_f32_e32 v109, 0xbfb8aa3b, v111
	v_exp_f32_e32 v109, v109
	s_nop 0
	v_add_f32_e32 v109, 1.0, v109
	v_rcp_f32_e32 v113, v109
	s_nop 0
	v_pk_mul_f32 v[110:111], v[112:113], v[110:111]
	s_nop 0
	v_pk_mul_f32 v[110:111], v[124:125], v[110:111]
	s_nop 0
	v_cvt_pk_bf16_f32 v109, v110, v111
	v_lshl_add_u64 v[110:111], s[64:65], 0, v[116:117]
	v_lshl_add_u64 v[110:111], v[110:111], 0, v[144:145]
	global_store_dwordx4 v[110:111], v[106:109], off offset:3072
	s_nop 1
	v_mov_b32_e32 v106, v218
	v_mov_b32_e32 v107, v219
	v_mov_b32_e32 v108, v220
	v_mov_b32_e32 v109, v221
	s_nop 0
	v_mov_b32_e32 v112, v190
	v_mov_b32_e32 v113, v191
	v_mov_b32_e32 v114, v192
	v_mov_b32_e32 v115, v193
	v_mov_b32_e32 v116, v186
	v_mov_b32_e32 v117, v187
	v_mov_b32_e32 v118, v188
	v_mov_b32_e32 v119, v189
	v_pk_fma_f32 v[116:117], v[140:141], v[116:117], v[102:103] op_sel_hi:[0,1,1]
	v_pk_fma_f32 v[102:103], v[140:141], v[114:115], v[100:101] op_sel_hi:[0,1,1]
	v_pk_fma_f32 v[100:101], v[140:141], v[112:113], v[98:99] op_sel_hi:[0,1,1]
	s_waitcnt lgkmcnt(0)
	v_lshlrev_b32_e32 v98, 16, v106
	v_and_b32_e32 v99, 0xffff0000, v106
	v_mul_f32_e32 v106, 0xbfb8aa3b, v98
	v_exp_f32_e32 v106, v106
	v_pk_fma_f32 v[104:105], v[140:141], v[118:119], v[104:105] op_sel_hi:[0,1,1]
	v_add_f32_e32 v106, 1.0, v106
	v_rcp_f32_e32 v112, v106
	v_mul_f32_e32 v106, 0xbfb8aa3b, v99
	v_exp_f32_e32 v106, v106
	s_nop 0
	v_add_f32_e32 v106, 1.0, v106
	v_rcp_f32_e32 v113, v106
	v_lshlrev_b32_e32 v106, 16, v107
	v_and_b32_e32 v107, 0xffff0000, v107
	v_pk_mul_f32 v[98:99], v[112:113], v[98:99]
	s_nop 0
	v_pk_mul_f32 v[98:99], v[116:117], v[98:99]
	s_nop 0
	v_cvt_pk_bf16_f32 v98, v98, v99
	v_mul_f32_e32 v99, 0xbfb8aa3b, v106
	v_exp_f32_e32 v99, v99
	s_nop 0
	v_add_f32_e32 v99, 1.0, v99
	v_rcp_f32_e32 v112, v99
	v_mul_f32_e32 v99, 0xbfb8aa3b, v107
	v_exp_f32_e32 v99, v99
	s_nop 0
	v_add_f32_e32 v99, 1.0, v99
	v_rcp_f32_e32 v113, v99
	s_nop 0
	v_pk_mul_f32 v[106:107], v[112:113], v[106:107]
	s_nop 0
	v_pk_mul_f32 v[104:105], v[104:105], v[106:107]
	s_nop 0
	v_cvt_pk_bf16_f32 v99, v104, v105
	v_lshlrev_b32_e32 v104, 16, v108
	v_and_b32_e32 v105, 0xffff0000, v108
	v_mul_f32_e32 v106, 0xbfb8aa3b, v104
	v_mul_f32_e32 v107, 0xbfb8aa3b, v105
	v_exp_f32_e32 v106, v106
	v_exp_f32_e32 v107, v107
	v_add_f32_e32 v106, 1.0, v106
	v_add_f32_e32 v107, 1.0, v107
	v_rcp_f32_e32 v106, v106
	v_rcp_f32_e32 v107, v107
	s_nop 0
	v_pk_mul_f32 v[104:105], v[106:107], v[104:105]
	s_nop 0
	v_pk_mul_f32 v[100:101], v[100:101], v[104:105]
	v_lshlrev_b32_e32 v104, 16, v109
	v_cvt_pk_bf16_f32 v100, v100, v101
	v_mul_f32_e32 v101, 0xbfb8aa3b, v104
	v_exp_f32_e32 v101, v101
	v_and_b32_e32 v105, 0xffff0000, v109
	v_add_f32_e32 v101, 1.0, v101
	v_rcp_f32_e32 v106, v101
	v_mul_f32_e32 v101, 0xbfb8aa3b, v105
	v_exp_f32_e32 v101, v101
	s_nop 0
	v_add_f32_e32 v101, 1.0, v101
	v_rcp_f32_e32 v107, v101
	s_nop 0
	v_pk_mul_f32 v[104:105], v[106:107], v[104:105]
	s_nop 0
	v_pk_mul_f32 v[102:103], v[102:103], v[104:105]
	s_nop 0
	v_cvt_pk_bf16_f32 v101, v102, v103
	global_store_dwordx4 v[110:111], v[98:101], off offset:3328
	s_nop 1
	s_nop 1
	v_add_u32_e32 v98, 32, v146
	v_ashrrev_i32_e32 v99, 31, v98
	v_lshlrev_b64 v[100:101], 12, v[98:99]
	v_mad_i64_i32 v[98:99], s[30:31], v98, s77, v[148:149]
	v_lshl_add_u64 v[98:99], v[98:99], 0, v[144:145]
	v_add_co_u32_e32 v98, vcc, s34, v98
	s_nop 1
	v_addc_co_u32_e32 v99, vcc, 0, v99, vcc
	v_mov_b32_e32 v102, v222
	v_mov_b32_e32 v103, v223
	v_mov_b32_e32 v104, v224
	v_mov_b32_e32 v105, v225
	v_mov_b32_e32 v106, v182
	v_mov_b32_e32 v107, v183
	v_mov_b32_e32 v108, v184
	v_mov_b32_e32 v109, v185
	v_mov_b32_e32 v110, v178
	v_mov_b32_e32 v111, v179
	v_mov_b32_e32 v112, v180
	v_mov_b32_e32 v113, v181
	v_pk_fma_f32 v[108:109], v[140:141], v[108:109], v[92:93] op_sel_hi:[0,1,1]
	v_pk_fma_f32 v[92:93], v[140:141], v[106:107], v[90:91] op_sel_hi:[0,1,1]
	s_waitcnt lgkmcnt(0)
	v_lshlrev_b32_e32 v90, 16, v102
	v_and_b32_e32 v91, 0xffff0000, v102
	v_mul_f32_e32 v102, 0xbfb8aa3b, v90
	v_exp_f32_e32 v102, v102
	v_pk_fma_f32 v[94:95], v[140:141], v[110:111], v[94:95] op_sel_hi:[0,1,1]
	v_pk_fma_f32 v[96:97], v[140:141], v[112:113], v[96:97] op_sel_hi:[0,1,1]
	v_add_f32_e32 v102, 1.0, v102
	v_rcp_f32_e32 v106, v102
	v_mul_f32_e32 v102, 0xbfb8aa3b, v91
	v_exp_f32_e32 v102, v102
	s_nop 0
	v_add_f32_e32 v102, 1.0, v102
	v_rcp_f32_e32 v107, v102
	s_nop 0
	v_pk_mul_f32 v[90:91], v[106:107], v[90:91]
	s_nop 0
	v_pk_mul_f32 v[90:91], v[94:95], v[90:91]
	v_lshlrev_b32_e32 v94, 16, v103
	v_cvt_pk_bf16_f32 v90, v90, v91
	v_mul_f32_e32 v91, 0xbfb8aa3b, v94
	v_exp_f32_e32 v91, v91
	v_and_b32_e32 v95, 0xffff0000, v103
	v_add_f32_e32 v91, 1.0, v91
	v_rcp_f32_e32 v102, v91
	v_mul_f32_e32 v91, 0xbfb8aa3b, v95
	v_exp_f32_e32 v91, v91
	s_nop 0
	v_add_f32_e32 v91, 1.0, v91
	v_rcp_f32_e32 v103, v91
	s_nop 0
	v_pk_mul_f32 v[94:95], v[102:103], v[94:95]
	s_nop 0
	v_pk_mul_f32 v[94:95], v[96:97], v[94:95]
	s_nop 0
	v_cvt_pk_bf16_f32 v91, v94, v95
	v_lshlrev_b32_e32 v94, 16, v104
	v_and_b32_e32 v95, 0xffff0000, v104
	v_mul_f32_e32 v96, 0xbfb8aa3b, v94
	v_mul_f32_e32 v97, 0xbfb8aa3b, v95
	v_exp_f32_e32 v96, v96
	v_exp_f32_e32 v97, v97
	v_add_f32_e32 v96, 1.0, v96
	v_add_f32_e32 v97, 1.0, v97
	v_rcp_f32_e32 v96, v96
	v_rcp_f32_e32 v97, v97
	s_nop 0
	v_pk_mul_f32 v[94:95], v[96:97], v[94:95]
	s_nop 0
	v_pk_mul_f32 v[92:93], v[92:93], v[94:95]
	v_lshlrev_b32_e32 v94, 16, v105
	v_cvt_pk_bf16_f32 v92, v92, v93
	v_mul_f32_e32 v93, 0xbfb8aa3b, v94
	v_exp_f32_e32 v93, v93
	v_and_b32_e32 v95, 0xffff0000, v105
	v_add_f32_e32 v93, 1.0, v93
	v_rcp_f32_e32 v96, v93
	v_mul_f32_e32 v93, 0xbfb8aa3b, v95
	v_exp_f32_e32 v93, v93
	s_nop 0
	v_add_f32_e32 v93, 1.0, v93
	v_rcp_f32_e32 v97, v93
	s_nop 0
	v_pk_mul_f32 v[94:95], v[96:97], v[94:95]
	s_nop 0
	v_pk_mul_f32 v[94:95], v[108:109], v[94:95]
	s_nop 0
	v_cvt_pk_bf16_f32 v93, v94, v95
	v_lshl_add_u64 v[94:95], s[64:65], 0, v[100:101]
	v_lshl_add_u64 v[94:95], v[94:95], 0, v[144:145]
	global_store_dwordx4 v[94:95], v[90:93], off offset:3072
	s_nop 1
	v_mov_b32_e32 v90, v226
	v_mov_b32_e32 v91, v227
	v_mov_b32_e32 v92, v228
	v_mov_b32_e32 v93, v229
	s_nop 0
	v_mov_b32_e32 v96, v190
	v_mov_b32_e32 v97, v191
	v_mov_b32_e32 v98, v192
	v_mov_b32_e32 v99, v193
	v_mov_b32_e32 v100, v186
	v_mov_b32_e32 v101, v187
	v_mov_b32_e32 v102, v188
	v_mov_b32_e32 v103, v189
	v_pk_fma_f32 v[100:101], v[140:141], v[100:101], v[86:87] op_sel_hi:[0,1,1]
	v_pk_fma_f32 v[86:87], v[140:141], v[98:99], v[84:85] op_sel_hi:[0,1,1]
	v_pk_fma_f32 v[84:85], v[140:141], v[96:97], v[82:83] op_sel_hi:[0,1,1]
	s_waitcnt lgkmcnt(0)
	v_lshlrev_b32_e32 v82, 16, v90
	v_and_b32_e32 v83, 0xffff0000, v90
	v_mul_f32_e32 v90, 0xbfb8aa3b, v82
	v_exp_f32_e32 v90, v90
	v_pk_fma_f32 v[88:89], v[140:141], v[102:103], v[88:89] op_sel_hi:[0,1,1]
	v_add_f32_e32 v90, 1.0, v90
	v_rcp_f32_e32 v96, v90
	v_mul_f32_e32 v90, 0xbfb8aa3b, v83
	v_exp_f32_e32 v90, v90
	s_nop 0
	v_add_f32_e32 v90, 1.0, v90
	v_rcp_f32_e32 v97, v90
	v_lshlrev_b32_e32 v90, 16, v91
	v_and_b32_e32 v91, 0xffff0000, v91
	v_pk_mul_f32 v[82:83], v[96:97], v[82:83]
	s_nop 0
	v_pk_mul_f32 v[82:83], v[100:101], v[82:83]
	s_nop 0
	v_cvt_pk_bf16_f32 v82, v82, v83
	v_mul_f32_e32 v83, 0xbfb8aa3b, v90
	v_exp_f32_e32 v83, v83
	s_nop 0
	v_add_f32_e32 v83, 1.0, v83
	v_rcp_f32_e32 v96, v83
	v_mul_f32_e32 v83, 0xbfb8aa3b, v91
	v_exp_f32_e32 v83, v83
	s_nop 0
	v_add_f32_e32 v83, 1.0, v83
	v_rcp_f32_e32 v97, v83
	s_nop 0
	v_pk_mul_f32 v[90:91], v[96:97], v[90:91]
	s_nop 0
	v_pk_mul_f32 v[88:89], v[88:89], v[90:91]
	s_nop 0
	v_cvt_pk_bf16_f32 v83, v88, v89
	v_lshlrev_b32_e32 v88, 16, v92
	v_and_b32_e32 v89, 0xffff0000, v92
	v_mul_f32_e32 v90, 0xbfb8aa3b, v88
	v_mul_f32_e32 v91, 0xbfb8aa3b, v89
	v_exp_f32_e32 v90, v90
	v_exp_f32_e32 v91, v91
	v_add_f32_e32 v90, 1.0, v90
	v_add_f32_e32 v91, 1.0, v91
	v_rcp_f32_e32 v90, v90
	v_rcp_f32_e32 v91, v91
	s_nop 0
	v_pk_mul_f32 v[88:89], v[90:91], v[88:89]
	s_nop 0
	v_pk_mul_f32 v[84:85], v[84:85], v[88:89]
	v_lshlrev_b32_e32 v88, 16, v93
	v_cvt_pk_bf16_f32 v84, v84, v85
	v_mul_f32_e32 v85, 0xbfb8aa3b, v88
	v_exp_f32_e32 v85, v85
	v_and_b32_e32 v89, 0xffff0000, v93
	v_add_f32_e32 v85, 1.0, v85
	v_rcp_f32_e32 v90, v85
	v_mul_f32_e32 v85, 0xbfb8aa3b, v89
	v_exp_f32_e32 v85, v85
	s_nop 0
	v_add_f32_e32 v85, 1.0, v85
	v_rcp_f32_e32 v91, v85
	s_nop 0
	v_pk_mul_f32 v[88:89], v[90:91], v[88:89]
	s_nop 0
	v_pk_mul_f32 v[86:87], v[86:87], v[88:89]
	s_nop 0
	v_cvt_pk_bf16_f32 v85, v86, v87
	global_store_dwordx4 v[94:95], v[82:85], off offset:3328
	s_nop 1
	s_nop 1
	v_add_u32_e32 v82, 48, v146
	v_ashrrev_i32_e32 v83, 31, v82
	v_lshlrev_b64 v[84:85], 12, v[82:83]
	v_mad_i64_i32 v[82:83], s[30:31], v82, s77, v[148:149]
	v_lshl_add_u64 v[82:83], v[82:83], 0, v[144:145]
	v_add_co_u32_e32 v82, vcc, s34, v82
	s_nop 1
	v_addc_co_u32_e32 v83, vcc, 0, v83, vcc
	v_mov_b32_e32 v86, v230
	v_mov_b32_e32 v87, v231
	v_mov_b32_e32 v88, v232
	v_mov_b32_e32 v89, v233
	v_mov_b32_e32 v90, v182
	v_mov_b32_e32 v91, v183
	v_mov_b32_e32 v92, v184
	v_mov_b32_e32 v93, v185
	v_mov_b32_e32 v94, v178
	v_mov_b32_e32 v95, v179
	v_mov_b32_e32 v96, v180
	v_mov_b32_e32 v97, v181
	v_pk_fma_f32 v[92:93], v[140:141], v[92:93], v[76:77] op_sel_hi:[0,1,1]
	v_pk_fma_f32 v[76:77], v[140:141], v[90:91], v[74:75] op_sel_hi:[0,1,1]
	s_waitcnt lgkmcnt(0)
	v_lshlrev_b32_e32 v74, 16, v86
	v_and_b32_e32 v75, 0xffff0000, v86
	v_mul_f32_e32 v86, 0xbfb8aa3b, v74
	v_exp_f32_e32 v86, v86
	v_pk_fma_f32 v[78:79], v[140:141], v[94:95], v[78:79] op_sel_hi:[0,1,1]
	v_pk_fma_f32 v[80:81], v[140:141], v[96:97], v[80:81] op_sel_hi:[0,1,1]
	v_add_f32_e32 v86, 1.0, v86
	v_rcp_f32_e32 v90, v86
	v_mul_f32_e32 v86, 0xbfb8aa3b, v75
	v_exp_f32_e32 v86, v86
	s_nop 0
	v_add_f32_e32 v86, 1.0, v86
	v_rcp_f32_e32 v91, v86
	s_nop 0
	v_pk_mul_f32 v[74:75], v[90:91], v[74:75]
	s_nop 0
	v_pk_mul_f32 v[74:75], v[78:79], v[74:75]
	v_lshlrev_b32_e32 v78, 16, v87
	v_cvt_pk_bf16_f32 v74, v74, v75
	v_mul_f32_e32 v75, 0xbfb8aa3b, v78
	v_exp_f32_e32 v75, v75
	v_and_b32_e32 v79, 0xffff0000, v87
	v_add_f32_e32 v75, 1.0, v75
	v_rcp_f32_e32 v86, v75
	v_mul_f32_e32 v75, 0xbfb8aa3b, v79
	v_exp_f32_e32 v75, v75
	s_nop 0
	v_add_f32_e32 v75, 1.0, v75
	v_rcp_f32_e32 v87, v75
	s_nop 0
	v_pk_mul_f32 v[78:79], v[86:87], v[78:79]
	s_nop 0
	v_pk_mul_f32 v[78:79], v[80:81], v[78:79]
	s_nop 0
	v_cvt_pk_bf16_f32 v75, v78, v79
	v_lshlrev_b32_e32 v78, 16, v88
	v_and_b32_e32 v79, 0xffff0000, v88
	v_mul_f32_e32 v80, 0xbfb8aa3b, v78
	v_mul_f32_e32 v81, 0xbfb8aa3b, v79
	v_exp_f32_e32 v80, v80
	v_exp_f32_e32 v81, v81
	v_add_f32_e32 v80, 1.0, v80
	v_add_f32_e32 v81, 1.0, v81
	v_rcp_f32_e32 v80, v80
	v_rcp_f32_e32 v81, v81
	s_nop 0
	v_pk_mul_f32 v[78:79], v[80:81], v[78:79]
	s_nop 0
	v_pk_mul_f32 v[76:77], v[76:77], v[78:79]
	v_lshlrev_b32_e32 v78, 16, v89
	v_cvt_pk_bf16_f32 v76, v76, v77
	v_mul_f32_e32 v77, 0xbfb8aa3b, v78
	v_exp_f32_e32 v77, v77
	v_and_b32_e32 v79, 0xffff0000, v89
	v_add_f32_e32 v77, 1.0, v77
	v_rcp_f32_e32 v80, v77
	v_mul_f32_e32 v77, 0xbfb8aa3b, v79
	v_exp_f32_e32 v77, v77
	s_nop 0
	v_add_f32_e32 v77, 1.0, v77
	v_rcp_f32_e32 v81, v77
	s_nop 0
	v_pk_mul_f32 v[78:79], v[80:81], v[78:79]
	s_nop 0
	v_pk_mul_f32 v[78:79], v[92:93], v[78:79]
	s_nop 0
	v_cvt_pk_bf16_f32 v77, v78, v79
	v_lshl_add_u64 v[78:79], s[64:65], 0, v[84:85]
	v_lshl_add_u64 v[78:79], v[78:79], 0, v[144:145]
	global_store_dwordx4 v[78:79], v[74:77], off offset:3072
	s_nop 1
	v_mov_b32_e32 v74, v196
	v_mov_b32_e32 v75, v197
	v_mov_b32_e32 v76, v198
	v_mov_b32_e32 v77, v199
	s_nop 0
	v_mov_b32_e32 v80, v190
	v_mov_b32_e32 v81, v191
	v_mov_b32_e32 v82, v192
	v_mov_b32_e32 v83, v193
	v_mov_b32_e32 v84, v186
	v_mov_b32_e32 v85, v187
	v_mov_b32_e32 v86, v188
	v_mov_b32_e32 v87, v189
	v_pk_fma_f32 v[84:85], v[140:141], v[84:85], v[70:71] op_sel_hi:[0,1,1]
	v_pk_fma_f32 v[70:71], v[140:141], v[82:83], v[68:69] op_sel_hi:[0,1,1]
	v_pk_fma_f32 v[68:69], v[140:141], v[80:81], v[66:67] op_sel_hi:[0,1,1]
	s_waitcnt lgkmcnt(0)
	v_lshlrev_b32_e32 v66, 16, v74
	v_and_b32_e32 v67, 0xffff0000, v74
	v_mul_f32_e32 v74, 0xbfb8aa3b, v66
	v_exp_f32_e32 v74, v74
	v_pk_fma_f32 v[72:73], v[140:141], v[86:87], v[72:73] op_sel_hi:[0,1,1]
	v_add_f32_e32 v74, 1.0, v74
	v_rcp_f32_e32 v80, v74
	v_mul_f32_e32 v74, 0xbfb8aa3b, v67
	v_exp_f32_e32 v74, v74
	s_nop 0
	v_add_f32_e32 v74, 1.0, v74
	v_rcp_f32_e32 v81, v74
	v_lshlrev_b32_e32 v74, 16, v75
	v_and_b32_e32 v75, 0xffff0000, v75
	v_pk_mul_f32 v[66:67], v[80:81], v[66:67]
	s_nop 0
	v_pk_mul_f32 v[66:67], v[84:85], v[66:67]
	s_nop 0
	v_cvt_pk_bf16_f32 v66, v66, v67
	v_mul_f32_e32 v67, 0xbfb8aa3b, v74
	v_exp_f32_e32 v67, v67
	s_nop 0
	v_add_f32_e32 v67, 1.0, v67
	v_rcp_f32_e32 v80, v67
	v_mul_f32_e32 v67, 0xbfb8aa3b, v75
	v_exp_f32_e32 v67, v67
	s_nop 0
	v_add_f32_e32 v67, 1.0, v67
	v_rcp_f32_e32 v81, v67
	s_nop 0
	v_pk_mul_f32 v[74:75], v[80:81], v[74:75]
	s_nop 0
	v_pk_mul_f32 v[72:73], v[72:73], v[74:75]
	s_nop 0
	v_cvt_pk_bf16_f32 v67, v72, v73
	v_lshlrev_b32_e32 v72, 16, v76
	v_and_b32_e32 v73, 0xffff0000, v76
	v_mul_f32_e32 v74, 0xbfb8aa3b, v72
	v_mul_f32_e32 v75, 0xbfb8aa3b, v73
	v_exp_f32_e32 v74, v74
	v_exp_f32_e32 v75, v75
	v_add_f32_e32 v74, 1.0, v74
	v_add_f32_e32 v75, 1.0, v75
	v_rcp_f32_e32 v74, v74
	v_rcp_f32_e32 v75, v75
	s_nop 0
	v_pk_mul_f32 v[72:73], v[74:75], v[72:73]
	s_nop 0
	v_pk_mul_f32 v[68:69], v[68:69], v[72:73]
	v_lshlrev_b32_e32 v72, 16, v77
	v_cvt_pk_bf16_f32 v68, v68, v69
	v_mul_f32_e32 v69, 0xbfb8aa3b, v72
	v_exp_f32_e32 v69, v69
	v_and_b32_e32 v73, 0xffff0000, v77
	v_add_f32_e32 v69, 1.0, v69
	v_rcp_f32_e32 v74, v69
	v_mul_f32_e32 v69, 0xbfb8aa3b, v73
	v_exp_f32_e32 v69, v69
	s_nop 0
	v_add_f32_e32 v69, 1.0, v69
	v_rcp_f32_e32 v75, v69
	s_nop 0
	v_pk_mul_f32 v[72:73], v[74:75], v[72:73]
	s_nop 0
	v_pk_mul_f32 v[70:71], v[70:71], v[72:73]
	s_nop 0
	v_cvt_pk_bf16_f32 v69, v70, v71
	global_store_dwordx4 v[78:79], v[66:69], off offset:3328
	s_nop 1
	s_nop 1
	v_add_u32_e32 v66, 0x80, v146
	v_ashrrev_i32_e32 v67, 31, v66
	v_lshlrev_b64 v[68:69], 12, v[66:67]
	v_mad_i64_i32 v[66:67], s[30:31], v66, s77, v[148:149]
	v_lshl_add_u64 v[66:67], v[66:67], 0, v[144:145]
	v_add_co_u32_e32 v66, vcc, s34, v66
	s_nop 1
	v_addc_co_u32_e32 v67, vcc, 0, v67, vcc
	v_add_co_u32_e32 v246, vcc, 0x140000, v194
	s_nop 1
	v_addc_co_u32_e32 v247, vcc, 0, v195, vcc
	global_load_dwordx4 v[206:209], v[246:247], off offset:1024
	global_load_dwordx4 v[210:213], v[246:247], off offset:1280
	v_add_co_u32_e32 v246, vcc, 0x168000, v194
	s_nop 1
	v_addc_co_u32_e32 v247, vcc, 0, v195, vcc
	global_load_dwordx4 v[214:217], v[246:247], off offset:1024
	global_load_dwordx4 v[218:221], v[246:247], off offset:1280
	v_add_co_u32_e32 v246, vcc, 0x190000, v194
	s_nop 1
	v_addc_co_u32_e32 v247, vcc, 0, v195, vcc
	global_load_dwordx4 v[222:225], v[246:247], off offset:1024
	global_load_dwordx4 v[226:229], v[246:247], off offset:1280
	v_add_co_u32_e32 v246, vcc, 0x1b8000, v194
	s_nop 1
	v_addc_co_u32_e32 v247, vcc, 0, v195, vcc
	global_load_dwordx4 v[230:233], v[246:247], off offset:1024
	global_load_dwordx4 v[196:199], v[246:247], off offset:1280
	s_waitcnt vmcnt(0)
	v_mov_b32_e32 v70, v206
	v_mov_b32_e32 v71, v207
	v_mov_b32_e32 v72, v208
	v_mov_b32_e32 v73, v209
	v_mov_b32_e32 v74, v182
	v_mov_b32_e32 v75, v183
	v_mov_b32_e32 v76, v184
	v_mov_b32_e32 v77, v185
	v_mov_b32_e32 v78, v178
	v_mov_b32_e32 v79, v179
	v_mov_b32_e32 v80, v180
	v_mov_b32_e32 v81, v181
	v_pk_fma_f32 v[76:77], v[140:141], v[76:77], v[60:61] op_sel_hi:[0,1,1]
	v_pk_fma_f32 v[60:61], v[140:141], v[74:75], v[58:59] op_sel_hi:[0,1,1]
	s_waitcnt lgkmcnt(0)
	v_lshlrev_b32_e32 v58, 16, v70
	v_and_b32_e32 v59, 0xffff0000, v70
	v_mul_f32_e32 v70, 0xbfb8aa3b, v58
	v_exp_f32_e32 v70, v70
	v_pk_fma_f32 v[62:63], v[140:141], v[78:79], v[62:63] op_sel_hi:[0,1,1]
	v_pk_fma_f32 v[64:65], v[140:141], v[80:81], v[64:65] op_sel_hi:[0,1,1]
	v_add_f32_e32 v70, 1.0, v70
	v_rcp_f32_e32 v74, v70
	v_mul_f32_e32 v70, 0xbfb8aa3b, v59
	v_exp_f32_e32 v70, v70
	s_nop 0
	v_add_f32_e32 v70, 1.0, v70
	v_rcp_f32_e32 v75, v70
	s_nop 0
	v_pk_mul_f32 v[58:59], v[74:75], v[58:59]
	s_nop 0
	v_pk_mul_f32 v[58:59], v[62:63], v[58:59]
	v_lshlrev_b32_e32 v62, 16, v71
	v_cvt_pk_bf16_f32 v58, v58, v59
	v_mul_f32_e32 v59, 0xbfb8aa3b, v62
	v_exp_f32_e32 v59, v59
	v_and_b32_e32 v63, 0xffff0000, v71
	v_add_f32_e32 v59, 1.0, v59
	v_rcp_f32_e32 v70, v59
	v_mul_f32_e32 v59, 0xbfb8aa3b, v63
	v_exp_f32_e32 v59, v59
	s_nop 0
	v_add_f32_e32 v59, 1.0, v59
	v_rcp_f32_e32 v71, v59
	s_nop 0
	v_pk_mul_f32 v[62:63], v[70:71], v[62:63]
	s_nop 0
	v_pk_mul_f32 v[62:63], v[64:65], v[62:63]
	s_nop 0
	v_cvt_pk_bf16_f32 v59, v62, v63
	v_lshlrev_b32_e32 v62, 16, v72
	v_and_b32_e32 v63, 0xffff0000, v72
	v_mul_f32_e32 v64, 0xbfb8aa3b, v62
	v_mul_f32_e32 v65, 0xbfb8aa3b, v63
	v_exp_f32_e32 v64, v64
	v_exp_f32_e32 v65, v65
	v_add_f32_e32 v64, 1.0, v64
	v_add_f32_e32 v65, 1.0, v65
	v_rcp_f32_e32 v64, v64
	v_rcp_f32_e32 v65, v65
	s_nop 0
	v_pk_mul_f32 v[62:63], v[64:65], v[62:63]
	s_nop 0
	v_pk_mul_f32 v[60:61], v[60:61], v[62:63]
	v_lshlrev_b32_e32 v62, 16, v73
	v_cvt_pk_bf16_f32 v60, v60, v61
	v_mul_f32_e32 v61, 0xbfb8aa3b, v62
	v_exp_f32_e32 v61, v61
	v_and_b32_e32 v63, 0xffff0000, v73
	v_add_f32_e32 v61, 1.0, v61
	v_rcp_f32_e32 v64, v61
	v_mul_f32_e32 v61, 0xbfb8aa3b, v63
	v_exp_f32_e32 v61, v61
	s_nop 0
	v_add_f32_e32 v61, 1.0, v61
	v_rcp_f32_e32 v65, v61
	s_nop 0
	v_pk_mul_f32 v[62:63], v[64:65], v[62:63]
	s_nop 0
	v_pk_mul_f32 v[62:63], v[76:77], v[62:63]
	s_nop 0
	v_cvt_pk_bf16_f32 v61, v62, v63
	v_lshl_add_u64 v[62:63], s[64:65], 0, v[68:69]
	v_lshl_add_u64 v[62:63], v[62:63], 0, v[144:145]
	global_store_dwordx4 v[62:63], v[58:61], off offset:3072
	s_nop 1
	v_mov_b32_e32 v58, v210
	v_mov_b32_e32 v59, v211
	v_mov_b32_e32 v60, v212
	v_mov_b32_e32 v61, v213
	s_nop 0
	v_mov_b32_e32 v64, v190
	v_mov_b32_e32 v65, v191
	v_mov_b32_e32 v66, v192
	v_mov_b32_e32 v67, v193
	v_mov_b32_e32 v68, v186
	v_mov_b32_e32 v69, v187
	v_mov_b32_e32 v70, v188
	v_mov_b32_e32 v71, v189
	v_pk_fma_f32 v[68:69], v[140:141], v[68:69], v[54:55] op_sel_hi:[0,1,1]
	v_pk_fma_f32 v[54:55], v[140:141], v[66:67], v[52:53] op_sel_hi:[0,1,1]
	v_pk_fma_f32 v[52:53], v[140:141], v[64:65], v[50:51] op_sel_hi:[0,1,1]
	s_waitcnt lgkmcnt(0)
	v_lshlrev_b32_e32 v50, 16, v58
	v_and_b32_e32 v51, 0xffff0000, v58
	v_mul_f32_e32 v58, 0xbfb8aa3b, v50
	v_exp_f32_e32 v58, v58
	v_pk_fma_f32 v[56:57], v[140:141], v[70:71], v[56:57] op_sel_hi:[0,1,1]
	v_add_f32_e32 v58, 1.0, v58
	v_rcp_f32_e32 v64, v58
	v_mul_f32_e32 v58, 0xbfb8aa3b, v51
	v_exp_f32_e32 v58, v58
	s_nop 0
	v_add_f32_e32 v58, 1.0, v58
	v_rcp_f32_e32 v65, v58
	v_lshlrev_b32_e32 v58, 16, v59
	v_and_b32_e32 v59, 0xffff0000, v59
	v_pk_mul_f32 v[50:51], v[64:65], v[50:51]
	s_nop 0
	v_pk_mul_f32 v[50:51], v[68:69], v[50:51]
	s_nop 0
	v_cvt_pk_bf16_f32 v50, v50, v51
	v_mul_f32_e32 v51, 0xbfb8aa3b, v58
	v_exp_f32_e32 v51, v51
	s_nop 0
	v_add_f32_e32 v51, 1.0, v51
	v_rcp_f32_e32 v64, v51
	v_mul_f32_e32 v51, 0xbfb8aa3b, v59
	v_exp_f32_e32 v51, v51
	s_nop 0
	v_add_f32_e32 v51, 1.0, v51
	v_rcp_f32_e32 v65, v51
	s_nop 0
	v_pk_mul_f32 v[58:59], v[64:65], v[58:59]
	s_nop 0
	v_pk_mul_f32 v[56:57], v[56:57], v[58:59]
	s_nop 0
	v_cvt_pk_bf16_f32 v51, v56, v57
	v_lshlrev_b32_e32 v56, 16, v60
	v_and_b32_e32 v57, 0xffff0000, v60
	v_mul_f32_e32 v58, 0xbfb8aa3b, v56
	v_mul_f32_e32 v59, 0xbfb8aa3b, v57
	v_exp_f32_e32 v58, v58
	v_exp_f32_e32 v59, v59
	v_add_f32_e32 v58, 1.0, v58
	v_add_f32_e32 v59, 1.0, v59
	v_rcp_f32_e32 v58, v58
	v_rcp_f32_e32 v59, v59
	s_nop 0
	v_pk_mul_f32 v[56:57], v[58:59], v[56:57]
	s_nop 0
	v_pk_mul_f32 v[52:53], v[52:53], v[56:57]
	v_lshlrev_b32_e32 v56, 16, v61
	v_cvt_pk_bf16_f32 v52, v52, v53
	v_mul_f32_e32 v53, 0xbfb8aa3b, v56
	v_exp_f32_e32 v53, v53
	v_and_b32_e32 v57, 0xffff0000, v61
	v_add_f32_e32 v53, 1.0, v53
	v_rcp_f32_e32 v58, v53
	v_mul_f32_e32 v53, 0xbfb8aa3b, v57
	v_exp_f32_e32 v53, v53
	s_nop 0
	v_add_f32_e32 v53, 1.0, v53
	v_rcp_f32_e32 v59, v53
	s_nop 0
	v_pk_mul_f32 v[56:57], v[58:59], v[56:57]
	s_nop 0
	v_pk_mul_f32 v[54:55], v[54:55], v[56:57]
	s_nop 0
	v_cvt_pk_bf16_f32 v53, v54, v55
	global_store_dwordx4 v[62:63], v[50:53], off offset:3328
	s_nop 1
	s_nop 1
	v_add_u32_e32 v50, 0x90, v146
	v_ashrrev_i32_e32 v51, 31, v50
	v_lshlrev_b64 v[52:53], 12, v[50:51]
	v_mad_i64_i32 v[50:51], s[30:31], v50, s77, v[148:149]
	v_lshl_add_u64 v[50:51], v[50:51], 0, v[144:145]
	v_add_co_u32_e32 v50, vcc, s34, v50
	s_nop 1
	v_addc_co_u32_e32 v51, vcc, 0, v51, vcc
	v_mov_b32_e32 v54, v214
	v_mov_b32_e32 v55, v215
	v_mov_b32_e32 v56, v216
	v_mov_b32_e32 v57, v217
	v_mov_b32_e32 v58, v182
	v_mov_b32_e32 v59, v183
	v_mov_b32_e32 v60, v184
	v_mov_b32_e32 v61, v185
	v_mov_b32_e32 v62, v178
	v_mov_b32_e32 v63, v179
	v_mov_b32_e32 v64, v180
	v_mov_b32_e32 v65, v181
	v_pk_fma_f32 v[60:61], v[140:141], v[60:61], v[44:45] op_sel_hi:[0,1,1]
	v_pk_fma_f32 v[44:45], v[140:141], v[58:59], v[42:43] op_sel_hi:[0,1,1]
	s_waitcnt lgkmcnt(0)
	v_lshlrev_b32_e32 v42, 16, v54
	v_and_b32_e32 v43, 0xffff0000, v54
	v_mul_f32_e32 v54, 0xbfb8aa3b, v42
	v_exp_f32_e32 v54, v54
	v_pk_fma_f32 v[46:47], v[140:141], v[62:63], v[46:47] op_sel_hi:[0,1,1]
	v_pk_fma_f32 v[48:49], v[140:141], v[64:65], v[48:49] op_sel_hi:[0,1,1]
	v_add_f32_e32 v54, 1.0, v54
	v_rcp_f32_e32 v58, v54
	v_mul_f32_e32 v54, 0xbfb8aa3b, v43
	v_exp_f32_e32 v54, v54
	s_nop 0
	v_add_f32_e32 v54, 1.0, v54
	v_rcp_f32_e32 v59, v54
	s_nop 0
	v_pk_mul_f32 v[42:43], v[58:59], v[42:43]
	s_nop 0
	v_pk_mul_f32 v[42:43], v[46:47], v[42:43]
	v_lshlrev_b32_e32 v46, 16, v55
	v_cvt_pk_bf16_f32 v42, v42, v43
	v_mul_f32_e32 v43, 0xbfb8aa3b, v46
	v_exp_f32_e32 v43, v43
	v_and_b32_e32 v47, 0xffff0000, v55
	v_add_f32_e32 v43, 1.0, v43
	v_rcp_f32_e32 v54, v43
	v_mul_f32_e32 v43, 0xbfb8aa3b, v47
	v_exp_f32_e32 v43, v43
	s_nop 0
	v_add_f32_e32 v43, 1.0, v43
	v_rcp_f32_e32 v55, v43
	s_nop 0
	v_pk_mul_f32 v[46:47], v[54:55], v[46:47]
	s_nop 0
	v_pk_mul_f32 v[46:47], v[48:49], v[46:47]
	s_nop 0
	v_cvt_pk_bf16_f32 v43, v46, v47
	v_lshlrev_b32_e32 v46, 16, v56
	v_and_b32_e32 v47, 0xffff0000, v56
	v_mul_f32_e32 v48, 0xbfb8aa3b, v46
	v_mul_f32_e32 v49, 0xbfb8aa3b, v47
	v_exp_f32_e32 v48, v48
	v_exp_f32_e32 v49, v49
	v_add_f32_e32 v48, 1.0, v48
	v_add_f32_e32 v49, 1.0, v49
	v_rcp_f32_e32 v48, v48
	v_rcp_f32_e32 v49, v49
	s_nop 0
	v_pk_mul_f32 v[46:47], v[48:49], v[46:47]
	s_nop 0
	v_pk_mul_f32 v[44:45], v[44:45], v[46:47]
	v_lshlrev_b32_e32 v46, 16, v57
	v_cvt_pk_bf16_f32 v44, v44, v45
	v_mul_f32_e32 v45, 0xbfb8aa3b, v46
	v_exp_f32_e32 v45, v45
	v_and_b32_e32 v47, 0xffff0000, v57
	v_add_f32_e32 v45, 1.0, v45
	v_rcp_f32_e32 v48, v45
	v_mul_f32_e32 v45, 0xbfb8aa3b, v47
	v_exp_f32_e32 v45, v45
	s_nop 0
	v_add_f32_e32 v45, 1.0, v45
	v_rcp_f32_e32 v49, v45
	s_nop 0
	v_pk_mul_f32 v[46:47], v[48:49], v[46:47]
	s_nop 0
	v_pk_mul_f32 v[46:47], v[60:61], v[46:47]
	s_nop 0
	v_cvt_pk_bf16_f32 v45, v46, v47
	v_lshl_add_u64 v[46:47], s[64:65], 0, v[52:53]
	v_lshl_add_u64 v[46:47], v[46:47], 0, v[144:145]
	global_store_dwordx4 v[46:47], v[42:45], off offset:3072
	s_nop 1
	v_mov_b32_e32 v42, v218
	v_mov_b32_e32 v43, v219
	v_mov_b32_e32 v44, v220
	v_mov_b32_e32 v45, v221
	s_nop 0
	v_mov_b32_e32 v48, v190
	v_mov_b32_e32 v49, v191
	v_mov_b32_e32 v50, v192
	v_mov_b32_e32 v51, v193
	v_mov_b32_e32 v52, v186
	v_mov_b32_e32 v53, v187
	v_mov_b32_e32 v54, v188
	v_mov_b32_e32 v55, v189
	v_pk_fma_f32 v[52:53], v[140:141], v[52:53], v[38:39] op_sel_hi:[0,1,1]
	v_pk_fma_f32 v[38:39], v[140:141], v[50:51], v[36:37] op_sel_hi:[0,1,1]
	v_pk_fma_f32 v[36:37], v[140:141], v[48:49], v[34:35] op_sel_hi:[0,1,1]
	s_waitcnt lgkmcnt(0)
	v_lshlrev_b32_e32 v34, 16, v42
	v_and_b32_e32 v35, 0xffff0000, v42
	v_mul_f32_e32 v42, 0xbfb8aa3b, v34
	v_exp_f32_e32 v42, v42
	v_pk_fma_f32 v[40:41], v[140:141], v[54:55], v[40:41] op_sel_hi:[0,1,1]
	v_add_f32_e32 v42, 1.0, v42
	v_rcp_f32_e32 v48, v42
	v_mul_f32_e32 v42, 0xbfb8aa3b, v35
	v_exp_f32_e32 v42, v42
	s_nop 0
	v_add_f32_e32 v42, 1.0, v42
	v_rcp_f32_e32 v49, v42
	v_lshlrev_b32_e32 v42, 16, v43
	v_and_b32_e32 v43, 0xffff0000, v43
	v_pk_mul_f32 v[34:35], v[48:49], v[34:35]
	s_nop 0
	v_pk_mul_f32 v[34:35], v[52:53], v[34:35]
	s_nop 0
	v_cvt_pk_bf16_f32 v34, v34, v35
	v_mul_f32_e32 v35, 0xbfb8aa3b, v42
	v_exp_f32_e32 v35, v35
	s_nop 0
	v_add_f32_e32 v35, 1.0, v35
	v_rcp_f32_e32 v48, v35
	v_mul_f32_e32 v35, 0xbfb8aa3b, v43
	v_exp_f32_e32 v35, v35
	s_nop 0
	v_add_f32_e32 v35, 1.0, v35
	v_rcp_f32_e32 v49, v35
	s_nop 0
	v_pk_mul_f32 v[42:43], v[48:49], v[42:43]
	s_nop 0
	v_pk_mul_f32 v[40:41], v[40:41], v[42:43]
	s_nop 0
	v_cvt_pk_bf16_f32 v35, v40, v41
	v_lshlrev_b32_e32 v40, 16, v44
	v_and_b32_e32 v41, 0xffff0000, v44
	v_mul_f32_e32 v42, 0xbfb8aa3b, v40
	v_mul_f32_e32 v43, 0xbfb8aa3b, v41
	v_exp_f32_e32 v42, v42
	v_exp_f32_e32 v43, v43
	v_add_f32_e32 v42, 1.0, v42
	v_add_f32_e32 v43, 1.0, v43
	v_rcp_f32_e32 v42, v42
	v_rcp_f32_e32 v43, v43
	s_nop 0
	v_pk_mul_f32 v[40:41], v[42:43], v[40:41]
	s_nop 0
	v_pk_mul_f32 v[36:37], v[36:37], v[40:41]
	v_lshlrev_b32_e32 v40, 16, v45
	v_cvt_pk_bf16_f32 v36, v36, v37
	v_mul_f32_e32 v37, 0xbfb8aa3b, v40
	v_exp_f32_e32 v37, v37
	v_and_b32_e32 v41, 0xffff0000, v45
	v_add_f32_e32 v37, 1.0, v37
	v_rcp_f32_e32 v42, v37
	v_mul_f32_e32 v37, 0xbfb8aa3b, v41
	v_exp_f32_e32 v37, v37
	s_nop 0
	v_add_f32_e32 v37, 1.0, v37
	v_rcp_f32_e32 v43, v37
	s_nop 0
	v_pk_mul_f32 v[40:41], v[42:43], v[40:41]
	s_nop 0
	v_pk_mul_f32 v[38:39], v[38:39], v[40:41]
	s_nop 0
	v_cvt_pk_bf16_f32 v37, v38, v39
	global_store_dwordx4 v[46:47], v[34:37], off offset:3328
	s_nop 1
	s_nop 1
	v_add_u32_e32 v34, 0xa0, v146
	v_ashrrev_i32_e32 v35, 31, v34
	v_lshlrev_b64 v[36:37], 12, v[34:35]
	v_mad_i64_i32 v[34:35], s[30:31], v34, s77, v[148:149]
	v_lshl_add_u64 v[34:35], v[34:35], 0, v[144:145]
	v_add_co_u32_e32 v34, vcc, s34, v34
	s_nop 1
	v_addc_co_u32_e32 v35, vcc, 0, v35, vcc
	v_mov_b32_e32 v38, v222
	v_mov_b32_e32 v39, v223
	v_mov_b32_e32 v40, v224
	v_mov_b32_e32 v41, v225
	v_mov_b32_e32 v42, v182
	v_mov_b32_e32 v43, v183
	v_mov_b32_e32 v44, v184
	v_mov_b32_e32 v45, v185
	v_mov_b32_e32 v46, v178
	v_mov_b32_e32 v47, v179
	v_mov_b32_e32 v48, v180
	v_mov_b32_e32 v49, v181
	v_pk_fma_f32 v[44:45], v[140:141], v[44:45], v[28:29] op_sel_hi:[0,1,1]
	v_pk_fma_f32 v[28:29], v[140:141], v[42:43], v[26:27] op_sel_hi:[0,1,1]
	s_waitcnt lgkmcnt(0)
	v_lshlrev_b32_e32 v26, 16, v38
	v_and_b32_e32 v27, 0xffff0000, v38
	v_mul_f32_e32 v38, 0xbfb8aa3b, v26
	v_exp_f32_e32 v38, v38
	v_pk_fma_f32 v[30:31], v[140:141], v[46:47], v[30:31] op_sel_hi:[0,1,1]
	v_pk_fma_f32 v[32:33], v[140:141], v[48:49], v[32:33] op_sel_hi:[0,1,1]
	v_add_f32_e32 v38, 1.0, v38
	v_rcp_f32_e32 v42, v38
	v_mul_f32_e32 v38, 0xbfb8aa3b, v27
	v_exp_f32_e32 v38, v38
	s_nop 0
	v_add_f32_e32 v38, 1.0, v38
	v_rcp_f32_e32 v43, v38
	s_nop 0
	v_pk_mul_f32 v[26:27], v[42:43], v[26:27]
	s_nop 0
	v_pk_mul_f32 v[26:27], v[30:31], v[26:27]
	v_lshlrev_b32_e32 v30, 16, v39
	v_cvt_pk_bf16_f32 v26, v26, v27
	v_mul_f32_e32 v27, 0xbfb8aa3b, v30
	v_exp_f32_e32 v27, v27
	v_and_b32_e32 v31, 0xffff0000, v39
	v_add_f32_e32 v27, 1.0, v27
	v_rcp_f32_e32 v38, v27
	v_mul_f32_e32 v27, 0xbfb8aa3b, v31
	v_exp_f32_e32 v27, v27
	s_nop 0
	v_add_f32_e32 v27, 1.0, v27
	v_rcp_f32_e32 v39, v27
	s_nop 0
	v_pk_mul_f32 v[30:31], v[38:39], v[30:31]
	s_nop 0
	v_pk_mul_f32 v[30:31], v[32:33], v[30:31]
	s_nop 0
	v_cvt_pk_bf16_f32 v27, v30, v31
	v_lshlrev_b32_e32 v30, 16, v40
	v_and_b32_e32 v31, 0xffff0000, v40
	v_mul_f32_e32 v32, 0xbfb8aa3b, v30
	v_mul_f32_e32 v33, 0xbfb8aa3b, v31
	v_exp_f32_e32 v32, v32
	v_exp_f32_e32 v33, v33
	v_add_f32_e32 v32, 1.0, v32
	v_add_f32_e32 v33, 1.0, v33
	v_rcp_f32_e32 v32, v32
	v_rcp_f32_e32 v33, v33
	s_nop 0
	v_pk_mul_f32 v[30:31], v[32:33], v[30:31]
	s_nop 0
	v_pk_mul_f32 v[28:29], v[28:29], v[30:31]
	v_lshlrev_b32_e32 v30, 16, v41
	v_cvt_pk_bf16_f32 v28, v28, v29
	v_mul_f32_e32 v29, 0xbfb8aa3b, v30
	v_exp_f32_e32 v29, v29
	v_and_b32_e32 v31, 0xffff0000, v41
	v_add_f32_e32 v29, 1.0, v29
	v_rcp_f32_e32 v32, v29
	v_mul_f32_e32 v29, 0xbfb8aa3b, v31
	v_exp_f32_e32 v29, v29
	s_nop 0
	v_add_f32_e32 v29, 1.0, v29
	v_rcp_f32_e32 v33, v29
	s_nop 0
	v_pk_mul_f32 v[30:31], v[32:33], v[30:31]
	s_nop 0
	v_pk_mul_f32 v[30:31], v[44:45], v[30:31]
	s_nop 0
	v_cvt_pk_bf16_f32 v29, v30, v31
	v_lshl_add_u64 v[30:31], s[64:65], 0, v[36:37]
	v_lshl_add_u64 v[30:31], v[30:31], 0, v[144:145]
	global_store_dwordx4 v[30:31], v[26:29], off offset:3072
	s_nop 1
	v_mov_b32_e32 v26, v226
	v_mov_b32_e32 v27, v227
	v_mov_b32_e32 v28, v228
	v_mov_b32_e32 v29, v229
	s_nop 0
	v_mov_b32_e32 v32, v190
	v_mov_b32_e32 v33, v191
	v_mov_b32_e32 v34, v192
	v_mov_b32_e32 v35, v193
	v_mov_b32_e32 v36, v186
	v_mov_b32_e32 v37, v187
	v_mov_b32_e32 v38, v188
	v_mov_b32_e32 v39, v189
	v_pk_fma_f32 v[36:37], v[140:141], v[36:37], v[22:23] op_sel_hi:[0,1,1]
	v_pk_fma_f32 v[22:23], v[140:141], v[34:35], v[20:21] op_sel_hi:[0,1,1]
	v_pk_fma_f32 v[20:21], v[140:141], v[32:33], v[18:19] op_sel_hi:[0,1,1]
	s_waitcnt lgkmcnt(0)
	v_lshlrev_b32_e32 v18, 16, v26
	v_and_b32_e32 v19, 0xffff0000, v26
	v_mul_f32_e32 v26, 0xbfb8aa3b, v18
	v_exp_f32_e32 v26, v26
	v_pk_fma_f32 v[24:25], v[140:141], v[38:39], v[24:25] op_sel_hi:[0,1,1]
	v_add_f32_e32 v26, 1.0, v26
	v_rcp_f32_e32 v32, v26
	v_mul_f32_e32 v26, 0xbfb8aa3b, v19
	v_exp_f32_e32 v26, v26
	s_nop 0
	v_add_f32_e32 v26, 1.0, v26
	v_rcp_f32_e32 v33, v26
	v_lshlrev_b32_e32 v26, 16, v27
	v_and_b32_e32 v27, 0xffff0000, v27
	v_pk_mul_f32 v[18:19], v[32:33], v[18:19]
	s_nop 0
	v_pk_mul_f32 v[18:19], v[36:37], v[18:19]
	s_nop 0
	v_cvt_pk_bf16_f32 v18, v18, v19
	v_mul_f32_e32 v19, 0xbfb8aa3b, v26
	v_exp_f32_e32 v19, v19
	s_nop 0
	v_add_f32_e32 v19, 1.0, v19
	v_rcp_f32_e32 v32, v19
	v_mul_f32_e32 v19, 0xbfb8aa3b, v27
	v_exp_f32_e32 v19, v19
	s_nop 0
	v_add_f32_e32 v19, 1.0, v19
	v_rcp_f32_e32 v33, v19
	s_nop 0
	v_pk_mul_f32 v[26:27], v[32:33], v[26:27]
	s_nop 0
	v_pk_mul_f32 v[24:25], v[24:25], v[26:27]
	s_nop 0
	v_cvt_pk_bf16_f32 v19, v24, v25
	v_lshlrev_b32_e32 v24, 16, v28
	v_and_b32_e32 v25, 0xffff0000, v28
	v_mul_f32_e32 v26, 0xbfb8aa3b, v24
	v_mul_f32_e32 v27, 0xbfb8aa3b, v25
	v_exp_f32_e32 v26, v26
	v_exp_f32_e32 v27, v27
	v_add_f32_e32 v26, 1.0, v26
	v_add_f32_e32 v27, 1.0, v27
	v_rcp_f32_e32 v26, v26
	v_rcp_f32_e32 v27, v27
	s_nop 0
	v_pk_mul_f32 v[24:25], v[26:27], v[24:25]
	s_nop 0
	v_pk_mul_f32 v[20:21], v[20:21], v[24:25]
	v_lshlrev_b32_e32 v24, 16, v29
	v_cvt_pk_bf16_f32 v20, v20, v21
	v_mul_f32_e32 v21, 0xbfb8aa3b, v24
	v_exp_f32_e32 v21, v21
	v_and_b32_e32 v25, 0xffff0000, v29
	v_add_f32_e32 v21, 1.0, v21
	v_rcp_f32_e32 v26, v21
	v_mul_f32_e32 v21, 0xbfb8aa3b, v25
	v_exp_f32_e32 v21, v21
	s_nop 0
	v_add_f32_e32 v21, 1.0, v21
	v_rcp_f32_e32 v27, v21
	s_nop 0
	v_pk_mul_f32 v[24:25], v[26:27], v[24:25]
	s_nop 0
	v_pk_mul_f32 v[22:23], v[22:23], v[24:25]
	s_nop 0
	v_cvt_pk_bf16_f32 v21, v22, v23
	global_store_dwordx4 v[30:31], v[18:21], off offset:3328
	s_nop 1
	s_nop 1
	v_add_u32_e32 v18, 0xb0, v146
	v_ashrrev_i32_e32 v19, 31, v18
	v_lshlrev_b64 v[20:21], 12, v[18:19]
	v_mad_i64_i32 v[18:19], s[30:31], v18, s77, v[148:149]
	v_lshl_add_u64 v[18:19], v[18:19], 0, v[144:145]
	v_add_co_u32_e32 v18, vcc, s34, v18
	s_nop 1
	v_addc_co_u32_e32 v19, vcc, 0, v19, vcc
	v_mov_b32_e32 v22, v230
	v_mov_b32_e32 v23, v231
	v_mov_b32_e32 v24, v232
	v_mov_b32_e32 v25, v233
	v_mov_b32_e32 v26, v182
	v_mov_b32_e32 v27, v183
	v_mov_b32_e32 v28, v184
	v_mov_b32_e32 v29, v185
	v_mov_b32_e32 v30, v178
	v_mov_b32_e32 v31, v179
	v_mov_b32_e32 v32, v180
	v_mov_b32_e32 v33, v181
	v_pk_fma_f32 v[28:29], v[140:141], v[28:29], v[12:13] op_sel_hi:[0,1,1]
	v_pk_fma_f32 v[12:13], v[140:141], v[26:27], v[10:11] op_sel_hi:[0,1,1]
	s_waitcnt lgkmcnt(0)
	v_lshlrev_b32_e32 v10, 16, v22
	v_and_b32_e32 v11, 0xffff0000, v22
	v_mul_f32_e32 v22, 0xbfb8aa3b, v10
	v_exp_f32_e32 v22, v22
	v_pk_fma_f32 v[14:15], v[140:141], v[30:31], v[14:15] op_sel_hi:[0,1,1]
	v_pk_fma_f32 v[16:17], v[140:141], v[32:33], v[16:17] op_sel_hi:[0,1,1]
	v_add_f32_e32 v22, 1.0, v22
	v_rcp_f32_e32 v26, v22
	v_mul_f32_e32 v22, 0xbfb8aa3b, v11
	v_exp_f32_e32 v22, v22
	s_nop 0
	v_add_f32_e32 v22, 1.0, v22
	v_rcp_f32_e32 v27, v22
	s_nop 0
	v_pk_mul_f32 v[10:11], v[26:27], v[10:11]
	s_nop 0
	v_pk_mul_f32 v[10:11], v[14:15], v[10:11]
	v_lshlrev_b32_e32 v14, 16, v23
	v_cvt_pk_bf16_f32 v10, v10, v11
	v_mul_f32_e32 v11, 0xbfb8aa3b, v14
	v_exp_f32_e32 v11, v11
	v_and_b32_e32 v15, 0xffff0000, v23
	v_add_f32_e32 v11, 1.0, v11
	v_rcp_f32_e32 v22, v11
	v_mul_f32_e32 v11, 0xbfb8aa3b, v15
	v_exp_f32_e32 v11, v11
	s_nop 0
	v_add_f32_e32 v11, 1.0, v11
	v_rcp_f32_e32 v23, v11
	s_nop 0
	v_pk_mul_f32 v[14:15], v[22:23], v[14:15]
	s_nop 0
	v_pk_mul_f32 v[14:15], v[16:17], v[14:15]
	s_nop 0
	v_cvt_pk_bf16_f32 v11, v14, v15
	v_lshlrev_b32_e32 v14, 16, v24
	v_and_b32_e32 v15, 0xffff0000, v24
	v_mul_f32_e32 v16, 0xbfb8aa3b, v14
	v_mul_f32_e32 v17, 0xbfb8aa3b, v15
	v_exp_f32_e32 v16, v16
	v_exp_f32_e32 v17, v17
	v_add_f32_e32 v16, 1.0, v16
	v_add_f32_e32 v17, 1.0, v17
	v_rcp_f32_e32 v16, v16
	v_rcp_f32_e32 v17, v17
	s_nop 0
	v_pk_mul_f32 v[14:15], v[16:17], v[14:15]
	s_nop 0
	v_pk_mul_f32 v[12:13], v[12:13], v[14:15]
	v_lshlrev_b32_e32 v14, 16, v25
	v_cvt_pk_bf16_f32 v12, v12, v13
	v_mul_f32_e32 v13, 0xbfb8aa3b, v14
	v_exp_f32_e32 v13, v13
	v_and_b32_e32 v15, 0xffff0000, v25
	v_add_f32_e32 v13, 1.0, v13
	v_rcp_f32_e32 v16, v13
	v_mul_f32_e32 v13, 0xbfb8aa3b, v15
	v_exp_f32_e32 v13, v13
	s_nop 0
	v_add_f32_e32 v13, 1.0, v13
	v_rcp_f32_e32 v17, v13
	s_nop 0
	v_pk_mul_f32 v[14:15], v[16:17], v[14:15]
	s_nop 0
	v_pk_mul_f32 v[14:15], v[28:29], v[14:15]
	s_nop 0
	v_cvt_pk_bf16_f32 v13, v14, v15
	v_lshl_add_u64 v[14:15], s[64:65], 0, v[20:21]
	v_lshl_add_u64 v[14:15], v[14:15], 0, v[144:145]
	global_store_dwordx4 v[14:15], v[10:13], off offset:3072
	s_nop 1
	v_mov_b32_e32 v10, v196
	v_mov_b32_e32 v11, v197
	v_mov_b32_e32 v12, v198
	v_mov_b32_e32 v13, v199
	s_nop 0
	v_mov_b32_e32 v16, v190
	v_mov_b32_e32 v17, v191
	v_mov_b32_e32 v18, v192
	v_mov_b32_e32 v19, v193
	v_mov_b32_e32 v20, v186
	v_mov_b32_e32 v21, v187
	v_mov_b32_e32 v22, v188
	v_mov_b32_e32 v23, v189
	v_pk_fma_f32 v[20:21], v[140:141], v[20:21], v[6:7] op_sel_hi:[0,1,1]
	v_pk_fma_f32 v[6:7], v[140:141], v[18:19], v[4:5] op_sel_hi:[0,1,1]
	v_pk_fma_f32 v[4:5], v[140:141], v[16:17], v[2:3] op_sel_hi:[0,1,1]
	s_waitcnt lgkmcnt(0)
	v_lshlrev_b32_e32 v2, 16, v10
	v_and_b32_e32 v3, 0xffff0000, v10
	v_mul_f32_e32 v10, 0xbfb8aa3b, v2
	v_exp_f32_e32 v10, v10
	v_pk_fma_f32 v[8:9], v[140:141], v[22:23], v[8:9] op_sel_hi:[0,1,1]
	v_add_f32_e32 v10, 1.0, v10
	v_rcp_f32_e32 v16, v10
	v_mul_f32_e32 v10, 0xbfb8aa3b, v3
	v_exp_f32_e32 v10, v10
	s_nop 0
	v_add_f32_e32 v10, 1.0, v10
	v_rcp_f32_e32 v17, v10
	v_lshlrev_b32_e32 v10, 16, v11
	v_and_b32_e32 v11, 0xffff0000, v11
	v_pk_mul_f32 v[2:3], v[16:17], v[2:3]
	s_nop 0
	v_pk_mul_f32 v[2:3], v[20:21], v[2:3]
	s_nop 0
	v_cvt_pk_bf16_f32 v2, v2, v3
	v_mul_f32_e32 v3, 0xbfb8aa3b, v10
	v_exp_f32_e32 v3, v3
	s_nop 0
	v_add_f32_e32 v3, 1.0, v3
	v_rcp_f32_e32 v16, v3
	v_mul_f32_e32 v3, 0xbfb8aa3b, v11
	v_exp_f32_e32 v3, v3
	s_nop 0
	v_add_f32_e32 v3, 1.0, v3
	v_rcp_f32_e32 v17, v3
	s_nop 0
	v_pk_mul_f32 v[10:11], v[16:17], v[10:11]
	s_nop 0
	v_pk_mul_f32 v[8:9], v[8:9], v[10:11]
	s_nop 0
	v_cvt_pk_bf16_f32 v3, v8, v9
	v_lshlrev_b32_e32 v8, 16, v12
	v_and_b32_e32 v9, 0xffff0000, v12
	v_mul_f32_e32 v10, 0xbfb8aa3b, v8
	v_mul_f32_e32 v11, 0xbfb8aa3b, v9
	v_exp_f32_e32 v10, v10
	v_exp_f32_e32 v11, v11
	v_add_f32_e32 v10, 1.0, v10
	v_add_f32_e32 v11, 1.0, v11
	v_rcp_f32_e32 v10, v10
	v_rcp_f32_e32 v11, v11
	s_nop 0
	v_pk_mul_f32 v[8:9], v[10:11], v[8:9]
	s_nop 0
	v_pk_mul_f32 v[4:5], v[4:5], v[8:9]
	v_lshlrev_b32_e32 v8, 16, v13
	v_cvt_pk_bf16_f32 v4, v4, v5
	v_mul_f32_e32 v5, 0xbfb8aa3b, v8
	v_exp_f32_e32 v5, v5
	v_and_b32_e32 v9, 0xffff0000, v13
	v_add_f32_e32 v5, 1.0, v5
	v_rcp_f32_e32 v10, v5
	v_mul_f32_e32 v5, 0xbfb8aa3b, v9
	v_exp_f32_e32 v5, v5
	s_nop 0
	v_add_f32_e32 v5, 1.0, v5
	v_rcp_f32_e32 v11, v5
	s_nop 0
	v_pk_mul_f32 v[8:9], v[10:11], v[8:9]
	s_nop 0
	v_pk_mul_f32 v[6:7], v[6:7], v[8:9]
	s_nop 0
	v_cvt_pk_bf16_f32 v5, v6, v7
	global_store_dwordx4 v[14:15], v[2:5], off offset:3328
	s_nop 1
	s_and_b64 vcc, exec, s[36:37]
	s_mov_b32 s87, s85
	s_mov_b32 s88, s86
	s_mov_b64 s[30:31], s[40:41]
	s_mov_b64 s[38:39], s[0:1]
	s_cbranch_vccnz .LBB0_763
